# phase_up conv epilogue: adjacent row pairs share the LDS window (8 reads instead of 12), scalar-stepped output base with saddr stores
# speedup vs baseline: 1.0080x; 1.0024x over previous
; #define WAIT_V0() asm volatile("s_waitcnt vmcnt(0)" ::: "memory")
; DI int glds_row(int i) { const int tid = ltid(); return ((tid >> 6) * 4 + i) * 8 + ((tid & 63) >> 3); }
; DI int glds_chunk(int row) { return (ltid() & 7) ^ ((row >> 1) & 7); }
; DI void gemm_core(char* smem, int nk, const char* Ab, const char* Bb, const unsigned (&aoff)[4], const unsigned (&boff)[4],
;                   f32x16 (&acc)[2][2]) {
;     ...
;   auto stage = [&](int buf, int kt) __attribute__((always_inline)) {
;     const char* ak = Ab + kt * 128;
;     const char* bk = Bb + kt * 128;
;     char* sa = smem + buf * STAGE_B + w * 4096;
; #pragma unroll
;     for (int i = 0; i < 4; ++i) {
;       __builtin_amdgcn_global_load_lds((const unsigned*)(ak + aoff[i]), (unsigned*)(sa + i * 1024), 16, 0, 0);
;       __builtin_amdgcn_global_load_lds((const unsigned*)(bk + boff[i]), (unsigned*)(sa + 16384 + i * 1024), 16, 0, 0);
;     }
;   };
;   stage(0, 0);
;   WAIT_V0();
;   __syncthreads();
; DI void phase_up(const Params& P, int layer, char* smem) {
;     ...
;   for (int t0 = blockIdx.x; t0 < MT * NT; t0 += gridDim.x) {
;     const int tl = xcd_tile(t0, MT * NT) - (t0 & 7) * ((MT * NT) >> 3);
;     const int mt = (t0 & 1) * 131 + tl / 11, nt = ((t0 & 7) >> 1) * 11 + tl % 11;
;     const int b = mt / 131, i = mt % 131;
;     const int tb0 = i * 126 - 2;
;     unsigned aoff[4], boff[4];
;     const char* Abase = (const char*)(hn + (size_t)b * S_ * 1024);
;     const unsigned zoff = (unsigned)((P.ws + OFF_ZPAGE) - Abase);
; #pragma unroll
;     for (int q = 0; q < 4; ++q) {
;       const int r = glds_row(q), ch = glds_chunk(r);
;       const int tb = tb0 + r;
;       const bool ok = (tb >= 0) && (tb < S_);
;       aoff[q] = ok ? (unsigned)((tb * 1024 + ch * 8) * 2) : zoff;
;       const int wr = (r < 64) ? (nt * 64 + r) : (DFF + nt * 64 + r - 64);
;       boff[q] = (unsigned)((wr * 1024 + ch * 8) * 2);
;     }
;     f32x16 acc[2][2];
;     gemm_core(smem, 16, Abase, (const char*)wup, aoff, boff, acc);
.LBB0_25:
	s_ashr_i32 s18, s2, 3
	s_and_b32 s19, s18, 0xffffffc0
	s_lshl_b32 s20, s18, 1
	s_bfe_u32 s21, s18, 0x10005
	s_and_b32 s20, s20, 62
	s_or_b32 s19, s21, s19
	s_or_b32 s19, s19, s20
	s_or_b32 s20, s18, 63
	s_cmpk_lt_i32 s20, 0x5a1
	s_cselect_b32 s18, s19, s18
	s_bitcmp1_b32 s2, 0
	s_mul_hi_i32 s20, s18, 0x2e8ba2e9
	s_cselect_b32 s19, 0x83, 0
	s_lshr_b32 s21, s20, 31
	s_ashr_i32 s20, s20, 1
	s_add_i32 s21, s20, s21
	s_add_i32 s20, s21, s19
	s_bfe_u32 s19, s2, 0x20001
	s_mul_i32 s21, s21, 11
	s_mul_i32 s19, s19, 11
	s_sub_i32 s18, s18, s21
	s_add_i32 s21, s18, s19
	s_mul_hi_i32 s18, s20, 0x3e88cb3d
	s_lshr_b32 s19, s18, 31
	s_ashr_i32 s18, s18, 5
	v_mov_b32_e32 v0, v161
	s_add_i32 s68, s18, s19
	s_mul_i32 s18, s68, 0x83
	v_ashrrev_i32_e32 v1, 1, v0
	v_lshrrev_b32_e32 v2, 3, v0
	v_bfe_u32 v0, v0, 3, 3
	s_movk_i32 s3, 0xffe0
	s_sub_i32 s28, s20, s18
	v_and_or_b32 v0, v1, s3, v0
	v_mov_b32_e32 v1, v161
	s_mulk_i32 s28, 0x7e
	s_ashr_i32 s69, s68, 31
	v_bfe_u32 v2, v2, 1, 2
	s_add_i32 s29, s28, -2
	s_lshl_b64 s[22:23], s[68:69], 25
	v_xor_b32_e32 v1, v2, v1
	s_add_u32 s18, s84, s22
	v_lshlrev_b32_e32 v1, 4, v1
	s_addc_u32 s19, s85, s23
	s_sub_i32 s22, 0x1b508000, s22
	s_lshl_b32 s21, s21, 6
	v_add_u32_e32 v2, s29, v0
	v_and_b32_e32 v1, 0x70, v1
	s_movk_i32 s3, 0x4000
	s_add_i32 s23, s21, 0xac0
	v_lshl_or_b32 v3, v2, 11, v1
	v_mov_b32_e32 v4, s22
	v_cmp_gt_u32_e32 vcc, s3, v2
	v_mov_b32_e32 v5, s21
	v_mov_b32_e32 v12, v161
	v_cndmask_b32_e32 v136, v4, v3, vcc
	v_mov_b32_e32 v3, s23
	v_cmp_gt_i32_e32 vcc, 64, v0
	v_lshl_add_u64 v[64:65], s[18:19], 0, v[136:137]
	s_mov_b64 s[4:5], 0x100
	v_cndmask_b32_e32 v2, v3, v5, vcc
	v_add_u32_e32 v0, v2, v0
	v_lshl_or_b32 v76, v0, 11, v1
	v_mov_b32_e32 v0, v161
	s_mov_b64 s[6:7], 0x780
	v_ashrrev_i32_e32 v1, 1, v0
	v_and_b32_e32 v1, 0xffffffe0, v1
	v_bfe_u32 v0, v0, 3, 3
	v_or3_b32 v1, v1, v0, 8
	v_mov_b32_e32 v0, v161
	v_lshrrev_b32_e32 v2, 1, v1
	v_xor_b32_e32 v0, v2, v0
	v_lshlrev_b32_e32 v0, 4, v0
	v_add_u32_e32 v2, s29, v1
	v_and_b32_e32 v6, 0x70, v0
	v_lshl_or_b32 v0, v2, 11, v6
	v_cmp_gt_u32_e32 vcc, s3, v2
	s_nop 1
	v_cndmask_b32_e32 v0, v4, v0, vcc
	v_cmp_gt_i32_e32 vcc, 64, v1
	s_nop 1
	v_cndmask_b32_e32 v2, v3, v5, vcc
	v_add_u32_e32 v1, v2, v1
	v_lshl_or_b32 v77, v1, 11, v6
	v_mov_b32_e32 v1, v161
	s_nop 0
	v_ashrrev_i32_e32 v2, 1, v1
	v_and_b32_e32 v2, 0xffffffe0, v2
	v_lshrrev_b32_e32 v6, 3, v1
	v_bfe_u32 v1, v1, 3, 3
	v_or3_b32 v1, v2, v1, 16
	v_mov_b32_e32 v2, v161
	v_bfe_u32 v6, v6, 1, 2
	v_xor_b32_e32 v2, v6, v2
	v_lshlrev_b32_e32 v2, 4, v2
	v_add_u32_e32 v6, s29, v1
	v_and_b32_e32 v7, 0x70, v2
	v_lshl_or_b32 v2, v6, 11, v7
	v_cmp_gt_u32_e32 vcc, s3, v6
	s_nop 1
	v_cndmask_b32_e32 v2, v4, v2, vcc
	v_cmp_gt_i32_e32 vcc, 64, v1
	s_nop 1
	v_cndmask_b32_e32 v6, v3, v5, vcc
	v_add_u32_e32 v1, v6, v1
	v_lshl_or_b32 v78, v1, 11, v7
	v_mov_b32_e32 v1, v161
	s_nop 0
	v_ashrrev_i32_e32 v6, 1, v1
	v_and_b32_e32 v6, 0xffffffe0, v6
	v_bfe_u32 v1, v1, 3, 3
	v_or3_b32 v1, v6, v1, 24
	v_mov_b32_e32 v6, v161
	v_lshrrev_b32_e32 v7, 1, v1
	v_xor_b32_e32 v6, v7, v6
	v_lshlrev_b32_e32 v6, 4, v6
	v_add_u32_e32 v7, s29, v1
	v_and_b32_e32 v6, 0x70, v6
	v_lshl_or_b32 v8, v7, 11, v6
	v_cmp_gt_u32_e32 vcc, s3, v7
	s_mov_b32 s3, 0x1ffffc0
	v_bfe_u32 v86, v12, 1, 3
	v_cndmask_b32_e32 v4, v4, v8, vcc
	v_cmp_gt_i32_e32 vcc, 64, v1
	v_bfe_u32 v117, v12, 5, 1
	s_nop 0
	v_cndmask_b32_e32 v3, v3, v5, vcc
	v_add_u32_e32 v1, v3, v1
	v_lshl_or_b32 v84, v1, 11, v6
	v_and_b32_e32 v1, 31, v12
	v_lshrrev_b32_e32 v5, 1, v12
	v_and_or_b32 v1, v5, s3, v1
	v_lshlrev_b32_e32 v87, 7, v1
	v_lshlrev_b32_e32 v1, 6, v12
	v_and_b32_e32 v97, 0xfffff000, v1
	v_add_u32_e32 v96, 0x4000, v97
	v_readfirstlane_b32 s84, v97
	s_mov_b32 m0, s84
	v_readfirstlane_b32 s85, v96
	v_or_b32_e32 v98, 0x400, v97
	global_load_lds_dwordx4 v136, s[18:19]
	s_mov_b32 m0, s85
	v_readfirstlane_b32 s86, v98
	v_add_u32_e32 v99, 0x4400, v97
	global_load_lds_dwordx4 v76, s[0:1]
	s_mov_b32 m0, s86
	v_readfirstlane_b32 s87, v99
	v_or_b32_e32 v100, 0x800, v97
	global_load_lds_dwordx4 v0, s[18:19]
	s_mov_b32 m0, s87
	v_readfirstlane_b32 s88, v100
	v_add_u32_e32 v101, 0x4800, v97
	v_lshrrev_b32_e32 v3, 5, v12
	global_load_lds_dwordx4 v77, s[0:1]
	s_mov_b32 m0, s88
	v_readfirstlane_b32 s89, v101
	v_or_b32_e32 v102, 0xc00, v97
	v_bitop3_b32 v3, v3, v86, 1 bitop3:0x6c
	global_load_lds_dwordx4 v2, s[18:19]
	s_mov_b32 m0, s89
	v_readfirstlane_b32 s90, v102
	v_add_u32_e32 v103, 0x4c00, v97
	v_lshlrev_b32_e32 v6, 4, v3
	v_mov_b32_e32 v1, v137
	v_mov_b32_e32 v3, v137
	global_load_lds_dwordx4 v78, s[0:1]
	v_mov_b32_e32 v5, v137
	s_mov_b32 m0, s90
	v_readfirstlane_b32 s91, v103
	v_add_u32_e32 v89, 0x8000, v97
	v_lshl_add_u64 v[66:67], s[18:19], 0, v[0:1]
	v_lshl_add_u64 v[68:69], s[18:19], 0, v[2:3]
	v_lshl_add_u64 v[70:71], s[18:19], 0, v[4:5]
	global_load_lds_dwordx4 v4, s[18:19]
	s_mov_b32 m0, s91
	v_add_u32_e32 v88, 0xc000, v97
	v_readfirstlane_b32 s18, v89
	global_load_lds_dwordx4 v84, s[0:1]
	v_lshl_add_u64 v[0:1], v[64:65], 0, s[94:95]
	s_mov_b32 m0, s18
	v_readfirstlane_b32 s19, v88
	v_add_u32_e32 v90, 0x8400, v97
	s_waitcnt vmcnt(0)
	s_waitcnt vmcnt(0) lgkmcnt(0)
	s_barrier
; #define WAIT_V0() asm volatile("s_waitcnt vmcnt(0)" ::: "memory")
; DI void gemm_core(char* smem, int nk, const char* Ab, const char* Bb, const unsigned (&aoff)[4], const unsigned (&boff)[4],
;                   f32x16 (&acc)[2][2]) {
;     ...
;   for (int kt = 0; kt < nk; ++kt) {
;     const int cur = kt & 1;
;     if (kt + 1 < nk) stage(cur ^ 1, kt + 1);
;     const char* sb = smem + cur * STAGE_B;
; #pragma unroll
;     for (int ks = 0; ks < 4; ++ks) {
;       bf16x8 af[2], bfr[2];
; #pragma unroll
;       for (int mb = 0; mb < 2; ++mb) af[mb] = *(const bf16x8*)(sb + a_base + mb * 4096 + xo[ks]);
; #pragma unroll
;       for (int nb = 0; nb < 2; ++nb) bfr[nb] = *(const bf16x8*)(sb + b_base + nb * 4096 + xo[ks]);
; #pragma unroll
;       for (int mb = 0; mb < 2; ++mb)
; #pragma unroll
;         for (int nb = 0; nb < 2; ++nb)
;           acc[mb][nb] = __builtin_amdgcn_mfma_f32_32x32x16_bf16(af[mb], bfr[nb], acc[mb][nb], 0, 0, 0);
;     }
;     WAIT_V0();
;     __syncthreads();
;   }
	global_load_lds_dwordx4 v[0:1], off
	s_mov_b32 m0, s19
	v_readfirstlane_b32 s22, v90
	v_add_u32_e32 v91, 0xc400, v97
	global_load_lds_dwordx4 v76, s[14:15]
	v_lshl_add_u64 v[0:1], v[66:67], 0, s[94:95]
	s_mov_b32 m0, s22
	v_readfirstlane_b32 s23, v91
	v_add_u32_e32 v92, 0x8800, v97
	global_load_lds_dwordx4 v[0:1], off
	s_mov_b32 m0, s23
	v_readfirstlane_b32 s29, v92
	v_add_u32_e32 v93, 0xc800, v97
	global_load_lds_dwordx4 v77, s[14:15]
	v_lshl_add_u64 v[0:1], v[68:69], 0, s[94:95]
	s_mov_b32 m0, s29
	v_readfirstlane_b32 s69, v93
	v_add_u32_e32 v94, 0x8c00, v97
	global_load_lds_dwordx4 v[0:1], off
	s_mov_b32 m0, s69
	v_readfirstlane_b32 s70, v94
	v_add_u32_e32 v95, 0xcc00, v97
	global_load_lds_dwordx4 v78, s[14:15]
	v_lshl_add_u64 v[0:1], v[70:71], 0, s[94:95]
	s_mov_b32 m0, s70
	v_readfirstlane_b32 s71, v95
	global_load_lds_dwordx4 v[0:1], off
	s_mov_b32 m0, s71
	v_or_b32_e32 v79, v87, v6
	global_load_lds_dwordx4 v84, s[14:15]
	ds_read_b128 v[0:3], v79
	v_lshlrev_b32_e32 v4, 7, v12
	v_and_b32_e32 v116, 0x2f80, v4
	v_or_b32_e32 v81, v116, v6
	ds_read_b128 v[4:7], v81 offset:16384
	ds_read_b128 v[8:11], v81 offset:20480
	s_waitcnt lgkmcnt(0)
	v_mfma_f32_32x32x16_bf16 v[48:63], v[0:3], v[4:7], 0
	s_mov_b32 m0, s84
	s_mov_b32 s3, 0xfffffc0
	v_mfma_f32_32x32x16_bf16 v[32:47], v[0:3], v[8:11], 0
	ds_read_b128 v[0:3], v79 offset:4096
	s_waitcnt lgkmcnt(0)
	v_mfma_f32_32x32x16_bf16 v[16:31], v[0:3], v[4:7], 0
	v_bitop3_b32 v4, v117, v86, 2 bitop3:0x36
	v_lshlrev_b32_e32 v82, 4, v4
	v_or_b32_e32 v80, v87, v82
	ds_read_b128 v[104:107], v80
	v_or_b32_e32 v83, v116, v82
	ds_read_b128 v[108:111], v83 offset:16384
	ds_read_b128 v[112:115], v83 offset:20480
	s_waitcnt lgkmcnt(0)
	v_mfma_f32_32x32x16_bf16 v[48:63], v[104:107], v[108:111], v[48:63]
	v_bitop3_b32 v82, v117, v86, 4 bitop3:0x36
	v_lshlrev_b32_e32 v85, 4, v82
	v_or_b32_e32 v82, v87, v85
	v_or_b32_e32 v85, v116, v85
	v_bitop3_b32 v86, v117, v86, 6 bitop3:0x36
	v_mfma_f32_32x32x16_bf16 v[32:47], v[104:107], v[112:115], v[32:47]
	ds_read_b128 v[104:107], v80 offset:4096
	v_mfma_f32_32x32x16_bf16 v[0:15], v[0:3], v[8:11], 0
	s_waitcnt lgkmcnt(0)
	v_mfma_f32_32x32x16_bf16 v[16:31], v[104:107], v[108:111], v[16:31]
	ds_read_b128 v[108:111], v85 offset:16384
	v_mfma_f32_32x32x16_bf16 v[0:15], v[104:107], v[112:115], v[0:15]
	ds_read_b128 v[104:107], v82
	ds_read_b128 v[112:115], v85 offset:20480
	s_waitcnt lgkmcnt(0)
	v_mfma_f32_32x32x16_bf16 v[48:63], v[104:107], v[108:111], v[48:63]
	v_mfma_f32_32x32x16_bf16 v[32:47], v[104:107], v[112:115], v[32:47]
	ds_read_b128 v[104:107], v82 offset:4096
	s_waitcnt lgkmcnt(0)
	v_mfma_f32_32x32x16_bf16 v[16:31], v[104:107], v[108:111], v[16:31]
	v_lshlrev_b32_e32 v108, 4, v86
	v_or_b32_e32 v86, v87, v108
	v_or_b32_e32 v87, v116, v108
	ds_read_b128 v[108:111], v87 offset:16384
	v_mfma_f32_32x32x16_bf16 v[0:15], v[104:107], v[112:115], v[0:15]
	ds_read_b128 v[104:107], v86
	ds_read_b128 v[112:115], v87 offset:20480
	s_waitcnt lgkmcnt(0)
	v_mfma_f32_32x32x16_bf16 v[48:63], v[104:107], v[108:111], v[48:63]
	v_mfma_f32_32x32x16_bf16 v[32:47], v[104:107], v[112:115], v[32:47]
	ds_read_b128 v[104:107], v86 offset:4096
	s_waitcnt vmcnt(0)
	s_waitcnt vmcnt(0) lgkmcnt(0)
	s_barrier
	v_mfma_f32_32x32x16_bf16 v[16:31], v[104:107], v[108:111], v[16:31]
	v_mfma_f32_32x32x16_bf16 v[0:15], v[104:107], v[112:115], v[0:15]
	v_lshl_add_u64 v[104:105], v[64:65], 0, s[4:5]
	global_load_lds_dwordx4 v[104:105], off
	s_mov_b32 m0, s85
	v_lshl_add_u64 v[104:105], v[66:67], 0, s[4:5]
	global_load_lds_dwordx4 v76, s[16:17]
	s_mov_b32 m0, s86
	s_nop 0
	global_load_lds_dwordx4 v[104:105], off
	s_mov_b32 m0, s87
	v_lshl_add_u64 v[104:105], v[68:69], 0, s[4:5]
	global_load_lds_dwordx4 v77, s[16:17]
	s_mov_b32 m0, s88
	s_nop 0
	global_load_lds_dwordx4 v[104:105], off
	s_mov_b32 m0, s89
	v_lshl_add_u64 v[104:105], v[70:71], 0, s[4:5]
	global_load_lds_dwordx4 v78, s[16:17]
	s_mov_b32 m0, s90
	s_mov_b64 s[4:5], 0x180
	global_load_lds_dwordx4 v[104:105], off
	s_mov_b32 m0, s91
	s_nop 0
	global_load_lds_dwordx4 v84, s[16:17]
	ds_read_b128 v[104:107], v79 offset:32768
	ds_read_b128 v[108:111], v81 offset:49152
	ds_read_b128 v[112:115], v81 offset:53248
	s_waitcnt lgkmcnt(0)
	v_mfma_f32_32x32x16_bf16 v[48:63], v[104:107], v[108:111], v[48:63]
	s_mov_b32 m0, s18
	v_mfma_f32_32x32x16_bf16 v[32:47], v[104:107], v[112:115], v[32:47]
	ds_read_b128 v[104:107], v79 offset:36864
	s_waitcnt lgkmcnt(0)
	v_mfma_f32_32x32x16_bf16 v[16:31], v[104:107], v[108:111], v[16:31]
	v_mfma_f32_32x32x16_bf16 v[0:15], v[104:107], v[112:115], v[0:15]
	ds_read_b128 v[104:107], v80 offset:32768
	ds_read_b128 v[108:111], v83 offset:49152
	ds_read_b128 v[112:115], v83 offset:53248
	s_waitcnt lgkmcnt(0)
	v_mfma_f32_32x32x16_bf16 v[48:63], v[104:107], v[108:111], v[48:63]
	v_mfma_f32_32x32x16_bf16 v[32:47], v[104:107], v[112:115], v[32:47]
	ds_read_b128 v[104:107], v80 offset:36864
	s_waitcnt lgkmcnt(0)
	v_mfma_f32_32x32x16_bf16 v[16:31], v[104:107], v[108:111], v[16:31]
	v_mfma_f32_32x32x16_bf16 v[0:15], v[104:107], v[112:115], v[0:15]
	ds_read_b128 v[104:107], v82 offset:32768
	ds_read_b128 v[108:111], v85 offset:49152
	ds_read_b128 v[112:115], v85 offset:53248
	s_waitcnt lgkmcnt(0)
	v_mfma_f32_32x32x16_bf16 v[48:63], v[104:107], v[108:111], v[48:63]
	v_mfma_f32_32x32x16_bf16 v[32:47], v[104:107], v[112:115], v[32:47]
	ds_read_b128 v[104:107], v82 offset:36864
	s_waitcnt lgkmcnt(0)
	v_mfma_f32_32x32x16_bf16 v[16:31], v[104:107], v[108:111], v[16:31]
	v_mfma_f32_32x32x16_bf16 v[0:15], v[104:107], v[112:115], v[0:15]
	ds_read_b128 v[104:107], v86 offset:32768
	ds_read_b128 v[108:111], v87 offset:49152
	ds_read_b128 v[112:115], v87 offset:53248
	s_waitcnt lgkmcnt(0)
	v_mfma_f32_32x32x16_bf16 v[48:63], v[104:107], v[108:111], v[48:63]
	v_mfma_f32_32x32x16_bf16 v[32:47], v[104:107], v[112:115], v[32:47]
	ds_read_b128 v[104:107], v86 offset:36864
	s_waitcnt vmcnt(0)
	s_waitcnt vmcnt(0) lgkmcnt(0)
	s_barrier
; #define WAIT_V0() asm volatile("s_waitcnt vmcnt(0)" ::: "memory")
; DI void gemm_core(char* smem, int nk, const char* Ab, const char* Bb, const unsigned (&aoff)[4], const unsigned (&boff)[4],
;                   f32x16 (&acc)[2][2]) {
;     ...
;   for (int kt = 0; kt < nk; ++kt) {
;     const int cur = kt & 1;
;     if (kt + 1 < nk) stage(cur ^ 1, kt + 1);
;     const char* sb = smem + cur * STAGE_B;
; #pragma unroll
;     for (int ks = 0; ks < 4; ++ks) {
;       bf16x8 af[2], bfr[2];
; #pragma unroll
;       for (int mb = 0; mb < 2; ++mb) af[mb] = *(const bf16x8*)(sb + a_base + mb * 4096 + xo[ks]);
; #pragma unroll
;       for (int nb = 0; nb < 2; ++nb) bfr[nb] = *(const bf16x8*)(sb + b_base + nb * 4096 + xo[ks]);
; #pragma unroll
;       for (int mb = 0; mb < 2; ++mb)
; #pragma unroll
;         for (int nb = 0; nb < 2; ++nb)
;           acc[mb][nb] = __builtin_amdgcn_mfma_f32_32x32x16_bf16(af[mb], bfr[nb], acc[mb][nb], 0, 0, 0);
;     }
;     WAIT_V0();
;     __syncthreads();
;   }
	v_mfma_f32_32x32x16_bf16 v[16:31], v[104:107], v[108:111], v[16:31]
	v_mfma_f32_32x32x16_bf16 v[0:15], v[104:107], v[112:115], v[0:15]
	v_lshl_add_u64 v[104:105], v[64:65], 0, s[4:5]
	global_load_lds_dwordx4 v[104:105], off
	s_mov_b32 m0, s19
	v_lshl_add_u64 v[104:105], v[66:67], 0, s[4:5]
	global_load_lds_dwordx4 v76, s[42:43]
	s_mov_b32 m0, s22
	s_nop 0
	global_load_lds_dwordx4 v[104:105], off
	s_mov_b32 m0, s23
	v_lshl_add_u64 v[104:105], v[68:69], 0, s[4:5]
	global_load_lds_dwordx4 v77, s[42:43]
	s_mov_b32 m0, s29
	s_nop 0
	global_load_lds_dwordx4 v[104:105], off
	s_mov_b32 m0, s69
	v_lshl_add_u64 v[104:105], v[70:71], 0, s[4:5]
	global_load_lds_dwordx4 v78, s[42:43]
	s_mov_b32 m0, s70
	s_mov_b64 s[4:5], 0x280
	global_load_lds_dwordx4 v[104:105], off
	s_mov_b32 m0, s71
	s_nop 0
	global_load_lds_dwordx4 v84, s[42:43]
	ds_read_b128 v[104:107], v79
	ds_read_b128 v[108:111], v81 offset:16384
	ds_read_b128 v[112:115], v81 offset:20480
	s_waitcnt lgkmcnt(0)
	v_mfma_f32_32x32x16_bf16 v[48:63], v[104:107], v[108:111], v[48:63]
	s_mov_b32 m0, s84
	v_mfma_f32_32x32x16_bf16 v[32:47], v[104:107], v[112:115], v[32:47]
	ds_read_b128 v[104:107], v79 offset:4096
	s_waitcnt lgkmcnt(0)
	v_mfma_f32_32x32x16_bf16 v[16:31], v[104:107], v[108:111], v[16:31]
	v_mfma_f32_32x32x16_bf16 v[0:15], v[104:107], v[112:115], v[0:15]
	ds_read_b128 v[104:107], v80
	ds_read_b128 v[108:111], v83 offset:16384
	ds_read_b128 v[112:115], v83 offset:20480
	s_waitcnt lgkmcnt(0)
	v_mfma_f32_32x32x16_bf16 v[48:63], v[104:107], v[108:111], v[48:63]
	v_mfma_f32_32x32x16_bf16 v[32:47], v[104:107], v[112:115], v[32:47]
	ds_read_b128 v[104:107], v80 offset:4096
	s_waitcnt lgkmcnt(0)
	v_mfma_f32_32x32x16_bf16 v[16:31], v[104:107], v[108:111], v[16:31]
	v_mfma_f32_32x32x16_bf16 v[0:15], v[104:107], v[112:115], v[0:15]
	ds_read_b128 v[104:107], v82
	ds_read_b128 v[108:111], v85 offset:16384
	ds_read_b128 v[112:115], v85 offset:20480
	s_waitcnt lgkmcnt(0)
	v_mfma_f32_32x32x16_bf16 v[48:63], v[104:107], v[108:111], v[48:63]
	v_mfma_f32_32x32x16_bf16 v[32:47], v[104:107], v[112:115], v[32:47]
	ds_read_b128 v[104:107], v82 offset:4096
	s_waitcnt lgkmcnt(0)
	v_mfma_f32_32x32x16_bf16 v[16:31], v[104:107], v[108:111], v[16:31]
	v_mfma_f32_32x32x16_bf16 v[0:15], v[104:107], v[112:115], v[0:15]
	ds_read_b128 v[104:107], v86
	ds_read_b128 v[108:111], v87 offset:16384
	ds_read_b128 v[112:115], v87 offset:20480
	s_waitcnt lgkmcnt(0)
	v_mfma_f32_32x32x16_bf16 v[48:63], v[104:107], v[108:111], v[48:63]
	v_mfma_f32_32x32x16_bf16 v[32:47], v[104:107], v[112:115], v[32:47]
	ds_read_b128 v[104:107], v86 offset:4096
	s_waitcnt vmcnt(0)
	s_waitcnt vmcnt(0) lgkmcnt(0)
	s_barrier
	v_mfma_f32_32x32x16_bf16 v[16:31], v[104:107], v[108:111], v[16:31]
	v_mfma_f32_32x32x16_bf16 v[0:15], v[104:107], v[112:115], v[0:15]
	v_lshl_add_u64 v[104:105], v[64:65], 0, s[30:31]
	global_load_lds_dwordx4 v[104:105], off
	s_mov_b32 m0, s85
	v_lshl_add_u64 v[104:105], v[66:67], 0, s[30:31]
	global_load_lds_dwordx4 v76, s[44:45]
	s_mov_b32 m0, s86
	s_nop 0
	global_load_lds_dwordx4 v[104:105], off
	s_mov_b32 m0, s87
	v_lshl_add_u64 v[104:105], v[68:69], 0, s[30:31]
	global_load_lds_dwordx4 v77, s[44:45]
	s_mov_b32 m0, s88
	s_nop 0
	global_load_lds_dwordx4 v[104:105], off
	s_mov_b32 m0, s89
	v_lshl_add_u64 v[104:105], v[70:71], 0, s[30:31]
	global_load_lds_dwordx4 v78, s[44:45]
	s_mov_b32 m0, s90
	s_nop 0
	global_load_lds_dwordx4 v[104:105], off
	s_mov_b32 m0, s91
	s_nop 0
	global_load_lds_dwordx4 v84, s[44:45]
	ds_read_b128 v[104:107], v79 offset:32768
	ds_read_b128 v[108:111], v81 offset:49152
	ds_read_b128 v[112:115], v81 offset:53248
	s_waitcnt lgkmcnt(0)
	v_mfma_f32_32x32x16_bf16 v[48:63], v[104:107], v[108:111], v[48:63]
	s_mov_b32 m0, s18
	v_mfma_f32_32x32x16_bf16 v[32:47], v[104:107], v[112:115], v[32:47]
	ds_read_b128 v[104:107], v79 offset:36864
	s_waitcnt lgkmcnt(0)
	v_mfma_f32_32x32x16_bf16 v[16:31], v[104:107], v[108:111], v[16:31]
	v_mfma_f32_32x32x16_bf16 v[0:15], v[104:107], v[112:115], v[0:15]
	ds_read_b128 v[104:107], v80 offset:32768
	ds_read_b128 v[108:111], v83 offset:49152
	ds_read_b128 v[112:115], v83 offset:53248
	s_waitcnt lgkmcnt(0)
	v_mfma_f32_32x32x16_bf16 v[48:63], v[104:107], v[108:111], v[48:63]
	v_mfma_f32_32x32x16_bf16 v[32:47], v[104:107], v[112:115], v[32:47]
	ds_read_b128 v[104:107], v80 offset:36864
	s_waitcnt lgkmcnt(0)
	v_mfma_f32_32x32x16_bf16 v[16:31], v[104:107], v[108:111], v[16:31]
	v_mfma_f32_32x32x16_bf16 v[0:15], v[104:107], v[112:115], v[0:15]
	ds_read_b128 v[104:107], v82 offset:32768
	ds_read_b128 v[108:111], v85 offset:49152
	ds_read_b128 v[112:115], v85 offset:53248
	s_waitcnt lgkmcnt(0)
	v_mfma_f32_32x32x16_bf16 v[48:63], v[104:107], v[108:111], v[48:63]
	v_mfma_f32_32x32x16_bf16 v[32:47], v[104:107], v[112:115], v[32:47]
	ds_read_b128 v[104:107], v82 offset:36864
	s_waitcnt lgkmcnt(0)
	v_mfma_f32_32x32x16_bf16 v[16:31], v[104:107], v[108:111], v[16:31]
	v_mfma_f32_32x32x16_bf16 v[0:15], v[104:107], v[112:115], v[0:15]
	ds_read_b128 v[104:107], v86 offset:32768
	ds_read_b128 v[108:111], v87 offset:49152
	ds_read_b128 v[112:115], v87 offset:53248
	s_waitcnt lgkmcnt(0)
	v_mfma_f32_32x32x16_bf16 v[48:63], v[104:107], v[108:111], v[48:63]
	v_mfma_f32_32x32x16_bf16 v[32:47], v[104:107], v[112:115], v[32:47]
	ds_read_b128 v[104:107], v86 offset:36864
	s_waitcnt vmcnt(0)
	s_waitcnt vmcnt(0) lgkmcnt(0)
	s_barrier
; #define WAIT_V0() asm volatile("s_waitcnt vmcnt(0)" ::: "memory")
; DI void gemm_core(char* smem, int nk, const char* Ab, const char* Bb, const unsigned (&aoff)[4], const unsigned (&boff)[4],
;                   f32x16 (&acc)[2][2]) {
;     ...
;   for (int kt = 0; kt < nk; ++kt) {
;     const int cur = kt & 1;
;     if (kt + 1 < nk) stage(cur ^ 1, kt + 1);
;     const char* sb = smem + cur * STAGE_B;
; #pragma unroll
;     for (int ks = 0; ks < 4; ++ks) {
;       bf16x8 af[2], bfr[2];
; #pragma unroll
;       for (int mb = 0; mb < 2; ++mb) af[mb] = *(const bf16x8*)(sb + a_base + mb * 4096 + xo[ks]);
; #pragma unroll
;       for (int nb = 0; nb < 2; ++nb) bfr[nb] = *(const bf16x8*)(sb + b_base + nb * 4096 + xo[ks]);
; #pragma unroll
;       for (int mb = 0; mb < 2; ++mb)
; #pragma unroll
;         for (int nb = 0; nb < 2; ++nb)
;           acc[mb][nb] = __builtin_amdgcn_mfma_f32_32x32x16_bf16(af[mb], bfr[nb], acc[mb][nb], 0, 0, 0);
;     }
;     WAIT_V0();
;     __syncthreads();
;   }
	v_mfma_f32_32x32x16_bf16 v[16:31], v[104:107], v[108:111], v[16:31]
	v_mfma_f32_32x32x16_bf16 v[0:15], v[104:107], v[112:115], v[0:15]
	v_lshl_add_u64 v[104:105], v[64:65], 0, s[4:5]
	global_load_lds_dwordx4 v[104:105], off
	s_mov_b32 m0, s19
	v_lshl_add_u64 v[104:105], v[66:67], 0, s[4:5]
	global_load_lds_dwordx4 v76, s[46:47]
	s_mov_b32 m0, s22
	s_nop 0
	global_load_lds_dwordx4 v[104:105], off
	s_mov_b32 m0, s23
	v_lshl_add_u64 v[104:105], v[68:69], 0, s[4:5]
	global_load_lds_dwordx4 v77, s[46:47]
	s_mov_b32 m0, s29
	s_nop 0
	global_load_lds_dwordx4 v[104:105], off
	s_mov_b32 m0, s69
	v_lshl_add_u64 v[104:105], v[70:71], 0, s[4:5]
	global_load_lds_dwordx4 v78, s[46:47]
	s_mov_b32 m0, s70
	s_mov_b64 s[4:5], 0x300
	global_load_lds_dwordx4 v[104:105], off
	s_mov_b32 m0, s71
	s_nop 0
	global_load_lds_dwordx4 v84, s[46:47]
	ds_read_b128 v[104:107], v79
	ds_read_b128 v[108:111], v81 offset:16384
	ds_read_b128 v[112:115], v81 offset:20480
	s_waitcnt lgkmcnt(0)
	v_mfma_f32_32x32x16_bf16 v[48:63], v[104:107], v[108:111], v[48:63]
	s_mov_b32 m0, s84
	v_mfma_f32_32x32x16_bf16 v[32:47], v[104:107], v[112:115], v[32:47]
	ds_read_b128 v[104:107], v79 offset:4096
	s_waitcnt lgkmcnt(0)
	v_mfma_f32_32x32x16_bf16 v[16:31], v[104:107], v[108:111], v[16:31]
	v_mfma_f32_32x32x16_bf16 v[0:15], v[104:107], v[112:115], v[0:15]
	ds_read_b128 v[104:107], v80
	ds_read_b128 v[108:111], v83 offset:16384
	ds_read_b128 v[112:115], v83 offset:20480
	s_waitcnt lgkmcnt(0)
	v_mfma_f32_32x32x16_bf16 v[48:63], v[104:107], v[108:111], v[48:63]
	v_mfma_f32_32x32x16_bf16 v[32:47], v[104:107], v[112:115], v[32:47]
	ds_read_b128 v[104:107], v80 offset:4096
	s_waitcnt lgkmcnt(0)
	v_mfma_f32_32x32x16_bf16 v[16:31], v[104:107], v[108:111], v[16:31]
	v_mfma_f32_32x32x16_bf16 v[0:15], v[104:107], v[112:115], v[0:15]
	ds_read_b128 v[104:107], v82
	ds_read_b128 v[108:111], v85 offset:16384
	ds_read_b128 v[112:115], v85 offset:20480
	s_waitcnt lgkmcnt(0)
	v_mfma_f32_32x32x16_bf16 v[48:63], v[104:107], v[108:111], v[48:63]
	v_mfma_f32_32x32x16_bf16 v[32:47], v[104:107], v[112:115], v[32:47]
	ds_read_b128 v[104:107], v82 offset:4096
	s_waitcnt lgkmcnt(0)
	v_mfma_f32_32x32x16_bf16 v[16:31], v[104:107], v[108:111], v[16:31]
	v_mfma_f32_32x32x16_bf16 v[0:15], v[104:107], v[112:115], v[0:15]
	ds_read_b128 v[104:107], v86
	ds_read_b128 v[108:111], v87 offset:16384
	ds_read_b128 v[112:115], v87 offset:20480
	s_waitcnt lgkmcnt(0)
	v_mfma_f32_32x32x16_bf16 v[48:63], v[104:107], v[108:111], v[48:63]
	v_mfma_f32_32x32x16_bf16 v[32:47], v[104:107], v[112:115], v[32:47]
	ds_read_b128 v[104:107], v86 offset:4096
	s_waitcnt vmcnt(0)
	s_waitcnt vmcnt(0) lgkmcnt(0)
	s_barrier
	v_mfma_f32_32x32x16_bf16 v[16:31], v[104:107], v[108:111], v[16:31]
	v_mfma_f32_32x32x16_bf16 v[0:15], v[104:107], v[112:115], v[0:15]
	v_lshl_add_u64 v[104:105], v[64:65], 0, s[4:5]
	global_load_lds_dwordx4 v[104:105], off
	s_mov_b32 m0, s85
	v_lshl_add_u64 v[104:105], v[66:67], 0, s[4:5]
	global_load_lds_dwordx4 v76, s[48:49]
	s_mov_b32 m0, s86
	s_nop 0
	global_load_lds_dwordx4 v[104:105], off
	s_mov_b32 m0, s87
	v_lshl_add_u64 v[104:105], v[68:69], 0, s[4:5]
	global_load_lds_dwordx4 v77, s[48:49]
	s_mov_b32 m0, s88
	s_nop 0
	global_load_lds_dwordx4 v[104:105], off
	s_mov_b32 m0, s89
	v_lshl_add_u64 v[104:105], v[70:71], 0, s[4:5]
	global_load_lds_dwordx4 v78, s[48:49]
	s_mov_b32 m0, s90
	s_mov_b64 s[4:5], 0x380
	global_load_lds_dwordx4 v[104:105], off
	s_mov_b32 m0, s91
	s_nop 0
	global_load_lds_dwordx4 v84, s[48:49]
	ds_read_b128 v[104:107], v79 offset:32768
	ds_read_b128 v[108:111], v81 offset:49152
	ds_read_b128 v[112:115], v81 offset:53248
	s_waitcnt lgkmcnt(0)
	v_mfma_f32_32x32x16_bf16 v[48:63], v[104:107], v[108:111], v[48:63]
	s_mov_b32 m0, s18
	v_mfma_f32_32x32x16_bf16 v[32:47], v[104:107], v[112:115], v[32:47]
	ds_read_b128 v[104:107], v79 offset:36864
	s_waitcnt lgkmcnt(0)
	v_mfma_f32_32x32x16_bf16 v[16:31], v[104:107], v[108:111], v[16:31]
	v_mfma_f32_32x32x16_bf16 v[0:15], v[104:107], v[112:115], v[0:15]
	ds_read_b128 v[104:107], v80 offset:32768
	ds_read_b128 v[108:111], v83 offset:49152
	ds_read_b128 v[112:115], v83 offset:53248
	s_waitcnt lgkmcnt(0)
	v_mfma_f32_32x32x16_bf16 v[48:63], v[104:107], v[108:111], v[48:63]
	v_mfma_f32_32x32x16_bf16 v[32:47], v[104:107], v[112:115], v[32:47]
	ds_read_b128 v[104:107], v80 offset:36864
	s_waitcnt lgkmcnt(0)
	v_mfma_f32_32x32x16_bf16 v[16:31], v[104:107], v[108:111], v[16:31]
	v_mfma_f32_32x32x16_bf16 v[0:15], v[104:107], v[112:115], v[0:15]
	ds_read_b128 v[104:107], v82 offset:32768
	ds_read_b128 v[108:111], v85 offset:49152
	ds_read_b128 v[112:115], v85 offset:53248
	s_waitcnt lgkmcnt(0)
	v_mfma_f32_32x32x16_bf16 v[48:63], v[104:107], v[108:111], v[48:63]
	v_mfma_f32_32x32x16_bf16 v[32:47], v[104:107], v[112:115], v[32:47]
	ds_read_b128 v[104:107], v82 offset:36864
	s_waitcnt lgkmcnt(0)
	v_mfma_f32_32x32x16_bf16 v[16:31], v[104:107], v[108:111], v[16:31]
	v_mfma_f32_32x32x16_bf16 v[0:15], v[104:107], v[112:115], v[0:15]
	ds_read_b128 v[104:107], v86 offset:32768
	ds_read_b128 v[108:111], v87 offset:49152
	ds_read_b128 v[112:115], v87 offset:53248
	s_waitcnt lgkmcnt(0)
	v_mfma_f32_32x32x16_bf16 v[48:63], v[104:107], v[108:111], v[48:63]
	v_mfma_f32_32x32x16_bf16 v[32:47], v[104:107], v[112:115], v[32:47]
	ds_read_b128 v[104:107], v86 offset:36864
	s_waitcnt vmcnt(0)
	s_waitcnt vmcnt(0) lgkmcnt(0)
	s_barrier
; #define WAIT_V0() asm volatile("s_waitcnt vmcnt(0)" ::: "memory")
; DI void gemm_core(char* smem, int nk, const char* Ab, const char* Bb, const unsigned (&aoff)[4], const unsigned (&boff)[4],
;                   f32x16 (&acc)[2][2]) {
;     ...
;   for (int kt = 0; kt < nk; ++kt) {
;     const int cur = kt & 1;
;     if (kt + 1 < nk) stage(cur ^ 1, kt + 1);
;     const char* sb = smem + cur * STAGE_B;
; #pragma unroll
;     for (int ks = 0; ks < 4; ++ks) {
;       bf16x8 af[2], bfr[2];
; #pragma unroll
;       for (int mb = 0; mb < 2; ++mb) af[mb] = *(const bf16x8*)(sb + a_base + mb * 4096 + xo[ks]);
; #pragma unroll
;       for (int nb = 0; nb < 2; ++nb) bfr[nb] = *(const bf16x8*)(sb + b_base + nb * 4096 + xo[ks]);
; #pragma unroll
;       for (int mb = 0; mb < 2; ++mb)
; #pragma unroll
;         for (int nb = 0; nb < 2; ++nb)
;           acc[mb][nb] = __builtin_amdgcn_mfma_f32_32x32x16_bf16(af[mb], bfr[nb], acc[mb][nb], 0, 0, 0);
;     }
;     WAIT_V0();
;     __syncthreads();
;   }
	v_mfma_f32_32x32x16_bf16 v[16:31], v[104:107], v[108:111], v[16:31]
	v_mfma_f32_32x32x16_bf16 v[0:15], v[104:107], v[112:115], v[0:15]
	v_lshl_add_u64 v[104:105], v[64:65], 0, s[4:5]
	global_load_lds_dwordx4 v[104:105], off
	s_mov_b32 m0, s19
	v_lshl_add_u64 v[104:105], v[66:67], 0, s[4:5]
	global_load_lds_dwordx4 v76, s[50:51]
	s_mov_b32 m0, s22
	s_nop 0
	global_load_lds_dwordx4 v[104:105], off
	s_mov_b32 m0, s23
	v_lshl_add_u64 v[104:105], v[68:69], 0, s[4:5]
	global_load_lds_dwordx4 v77, s[50:51]
	s_mov_b32 m0, s29
	s_nop 0
	global_load_lds_dwordx4 v[104:105], off
	s_mov_b32 m0, s69
	v_lshl_add_u64 v[104:105], v[70:71], 0, s[4:5]
	global_load_lds_dwordx4 v78, s[50:51]
	s_mov_b32 m0, s70
	s_mov_b64 s[4:5], 0x400
	global_load_lds_dwordx4 v[104:105], off
	s_mov_b32 m0, s71
	s_nop 0
	global_load_lds_dwordx4 v84, s[50:51]
	ds_read_b128 v[104:107], v79
	ds_read_b128 v[108:111], v81 offset:16384
	ds_read_b128 v[112:115], v81 offset:20480
	s_waitcnt lgkmcnt(0)
	v_mfma_f32_32x32x16_bf16 v[48:63], v[104:107], v[108:111], v[48:63]
	s_mov_b32 m0, s84
	v_readfirstlane_b32 s84, v89
	v_mfma_f32_32x32x16_bf16 v[32:47], v[104:107], v[112:115], v[32:47]
	ds_read_b128 v[104:107], v79 offset:4096
	s_waitcnt lgkmcnt(0)
	v_mfma_f32_32x32x16_bf16 v[16:31], v[104:107], v[108:111], v[16:31]
	v_mfma_f32_32x32x16_bf16 v[0:15], v[104:107], v[112:115], v[0:15]
	ds_read_b128 v[104:107], v80
	ds_read_b128 v[108:111], v83 offset:16384
	ds_read_b128 v[112:115], v83 offset:20480
	s_waitcnt lgkmcnt(0)
	v_mfma_f32_32x32x16_bf16 v[48:63], v[104:107], v[108:111], v[48:63]
	v_mfma_f32_32x32x16_bf16 v[32:47], v[104:107], v[112:115], v[32:47]
	ds_read_b128 v[104:107], v80 offset:4096
	s_waitcnt lgkmcnt(0)
	v_mfma_f32_32x32x16_bf16 v[16:31], v[104:107], v[108:111], v[16:31]
	v_mfma_f32_32x32x16_bf16 v[0:15], v[104:107], v[112:115], v[0:15]
	ds_read_b128 v[104:107], v82
	ds_read_b128 v[108:111], v85 offset:16384
	ds_read_b128 v[112:115], v85 offset:20480
	s_waitcnt lgkmcnt(0)
	v_mfma_f32_32x32x16_bf16 v[48:63], v[104:107], v[108:111], v[48:63]
	v_mfma_f32_32x32x16_bf16 v[32:47], v[104:107], v[112:115], v[32:47]
	ds_read_b128 v[104:107], v82 offset:4096
	s_waitcnt lgkmcnt(0)
	v_mfma_f32_32x32x16_bf16 v[16:31], v[104:107], v[108:111], v[16:31]
	v_mfma_f32_32x32x16_bf16 v[0:15], v[104:107], v[112:115], v[0:15]
	ds_read_b128 v[104:107], v86
	ds_read_b128 v[108:111], v87 offset:16384
	ds_read_b128 v[112:115], v87 offset:20480
	s_waitcnt lgkmcnt(0)
	v_mfma_f32_32x32x16_bf16 v[48:63], v[104:107], v[108:111], v[48:63]
	v_mfma_f32_32x32x16_bf16 v[32:47], v[104:107], v[112:115], v[32:47]
	ds_read_b128 v[104:107], v86 offset:4096
	s_waitcnt vmcnt(0)
	s_waitcnt vmcnt(0) lgkmcnt(0)
	s_barrier
	v_mfma_f32_32x32x16_bf16 v[16:31], v[104:107], v[108:111], v[16:31]
	v_mfma_f32_32x32x16_bf16 v[0:15], v[104:107], v[112:115], v[0:15]
	v_lshl_add_u64 v[104:105], v[64:65], 0, s[4:5]
	global_load_lds_dwordx4 v[104:105], off
	s_mov_b32 m0, s85
	v_lshl_add_u64 v[104:105], v[66:67], 0, s[4:5]
	global_load_lds_dwordx4 v76, s[52:53]
	s_mov_b32 m0, s86
	v_readfirstlane_b32 s85, v88
	global_load_lds_dwordx4 v[104:105], off
	s_mov_b32 m0, s87
	v_lshl_add_u64 v[104:105], v[68:69], 0, s[4:5]
	global_load_lds_dwordx4 v77, s[52:53]
	s_mov_b32 m0, s88
	v_readfirstlane_b32 s86, v90
	global_load_lds_dwordx4 v[104:105], off
	s_mov_b32 m0, s89
	v_lshl_add_u64 v[104:105], v[70:71], 0, s[4:5]
	global_load_lds_dwordx4 v78, s[52:53]
	s_mov_b32 m0, s90
	s_mov_b64 s[4:5], 0x480
	global_load_lds_dwordx4 v[104:105], off
	s_mov_b32 m0, s91
	v_readfirstlane_b32 s87, v91
	global_load_lds_dwordx4 v84, s[52:53]
	ds_read_b128 v[104:107], v79 offset:32768
	ds_read_b128 v[108:111], v81 offset:49152
	ds_read_b128 v[112:115], v81 offset:53248
	s_waitcnt lgkmcnt(0)
	v_mfma_f32_32x32x16_bf16 v[48:63], v[104:107], v[108:111], v[48:63]
	s_mov_b32 m0, s18
	v_readfirstlane_b32 s18, v97
	v_readfirstlane_b32 s88, v92
	v_readfirstlane_b32 s89, v93
	v_readfirstlane_b32 s90, v94
	v_readfirstlane_b32 s91, v95
	v_mfma_f32_32x32x16_bf16 v[32:47], v[104:107], v[112:115], v[32:47]
	ds_read_b128 v[104:107], v79 offset:36864
	s_waitcnt lgkmcnt(0)
	v_mfma_f32_32x32x16_bf16 v[16:31], v[104:107], v[108:111], v[16:31]
	v_mfma_f32_32x32x16_bf16 v[0:15], v[104:107], v[112:115], v[0:15]
	ds_read_b128 v[104:107], v80 offset:32768
	ds_read_b128 v[108:111], v83 offset:49152
	ds_read_b128 v[112:115], v83 offset:53248
	s_waitcnt lgkmcnt(0)
	v_mfma_f32_32x32x16_bf16 v[48:63], v[104:107], v[108:111], v[48:63]
	v_mfma_f32_32x32x16_bf16 v[32:47], v[104:107], v[112:115], v[32:47]
	ds_read_b128 v[104:107], v80 offset:36864
	s_waitcnt lgkmcnt(0)
	v_mfma_f32_32x32x16_bf16 v[16:31], v[104:107], v[108:111], v[16:31]
	v_mfma_f32_32x32x16_bf16 v[0:15], v[104:107], v[112:115], v[0:15]
	ds_read_b128 v[104:107], v82 offset:32768
	ds_read_b128 v[108:111], v85 offset:49152
	ds_read_b128 v[112:115], v85 offset:53248
	s_waitcnt lgkmcnt(0)
	v_mfma_f32_32x32x16_bf16 v[48:63], v[104:107], v[108:111], v[48:63]
	v_mfma_f32_32x32x16_bf16 v[32:47], v[104:107], v[112:115], v[32:47]
	ds_read_b128 v[104:107], v82 offset:36864
	s_waitcnt lgkmcnt(0)
	v_mfma_f32_32x32x16_bf16 v[16:31], v[104:107], v[108:111], v[16:31]
	v_mfma_f32_32x32x16_bf16 v[0:15], v[104:107], v[112:115], v[0:15]
	ds_read_b128 v[104:107], v86 offset:32768
	ds_read_b128 v[108:111], v87 offset:49152
	ds_read_b128 v[112:115], v87 offset:53248
	s_waitcnt lgkmcnt(0)
	v_mfma_f32_32x32x16_bf16 v[48:63], v[104:107], v[108:111], v[48:63]
	v_mfma_f32_32x32x16_bf16 v[32:47], v[104:107], v[112:115], v[32:47]
	ds_read_b128 v[104:107], v86 offset:36864
	s_waitcnt vmcnt(0)
	s_waitcnt vmcnt(0) lgkmcnt(0)
	s_barrier
; #define WAIT_V0() asm volatile("s_waitcnt vmcnt(0)" ::: "memory")
; DI void gemm_core(char* smem, int nk, const char* Ab, const char* Bb, const unsigned (&aoff)[4], const unsigned (&boff)[4],
;                   f32x16 (&acc)[2][2]) {
;     ...
;   for (int kt = 0; kt < nk; ++kt) {
;     const int cur = kt & 1;
;     if (kt + 1 < nk) stage(cur ^ 1, kt + 1);
;     const char* sb = smem + cur * STAGE_B;
; #pragma unroll
;     for (int ks = 0; ks < 4; ++ks) {
;       bf16x8 af[2], bfr[2];
; #pragma unroll
;       for (int mb = 0; mb < 2; ++mb) af[mb] = *(const bf16x8*)(sb + a_base + mb * 4096 + xo[ks]);
; #pragma unroll
;       for (int nb = 0; nb < 2; ++nb) bfr[nb] = *(const bf16x8*)(sb + b_base + nb * 4096 + xo[ks]);
; #pragma unroll
;       for (int mb = 0; mb < 2; ++mb)
; #pragma unroll
;         for (int nb = 0; nb < 2; ++nb)
;           acc[mb][nb] = __builtin_amdgcn_mfma_f32_32x32x16_bf16(af[mb], bfr[nb], acc[mb][nb], 0, 0, 0);
;     }
;     WAIT_V0();
;     __syncthreads();
;   }
	v_mfma_f32_32x32x16_bf16 v[16:31], v[104:107], v[108:111], v[16:31]
	v_mfma_f32_32x32x16_bf16 v[0:15], v[104:107], v[112:115], v[0:15]
	v_lshl_add_u64 v[104:105], v[64:65], 0, s[4:5]
	global_load_lds_dwordx4 v[104:105], off
	s_mov_b32 m0, s19
	v_lshl_add_u64 v[104:105], v[66:67], 0, s[4:5]
	global_load_lds_dwordx4 v76, s[54:55]
	s_mov_b32 m0, s22
	v_readfirstlane_b32 s19, v96
	global_load_lds_dwordx4 v[104:105], off
	s_mov_b32 m0, s23
	v_lshl_add_u64 v[104:105], v[68:69], 0, s[4:5]
	global_load_lds_dwordx4 v77, s[54:55]
	s_mov_b32 m0, s29
	v_readfirstlane_b32 s22, v98
	global_load_lds_dwordx4 v[104:105], off
	s_mov_b32 m0, s69
	v_lshl_add_u64 v[104:105], v[70:71], 0, s[4:5]
	global_load_lds_dwordx4 v78, s[54:55]
	s_mov_b32 m0, s70
	s_mov_b64 s[4:5], 0x500
	global_load_lds_dwordx4 v[104:105], off
	s_mov_b32 m0, s71
	v_lshl_add_u64 v[96:97], v[66:67], 0, s[4:5]
	global_load_lds_dwordx4 v84, s[54:55]
	ds_read_b128 v[104:107], v79
	ds_read_b128 v[108:111], v81 offset:16384
	ds_read_b128 v[112:115], v81 offset:20480
	s_waitcnt lgkmcnt(0)
	v_mfma_f32_32x32x16_bf16 v[48:63], v[104:107], v[108:111], v[48:63]
	s_mov_b32 m0, s18
	v_readfirstlane_b32 s23, v99
	v_readfirstlane_b32 s29, v100
	v_readfirstlane_b32 s69, v101
	v_readfirstlane_b32 s70, v102
	v_readfirstlane_b32 s71, v103
	v_mfma_f32_32x32x16_bf16 v[32:47], v[104:107], v[112:115], v[32:47]
	ds_read_b128 v[104:107], v79 offset:4096
	s_waitcnt lgkmcnt(0)
	v_mfma_f32_32x32x16_bf16 v[16:31], v[104:107], v[108:111], v[16:31]
	v_mfma_f32_32x32x16_bf16 v[0:15], v[104:107], v[112:115], v[0:15]
	ds_read_b128 v[104:107], v80
	ds_read_b128 v[108:111], v83 offset:16384
	ds_read_b128 v[112:115], v83 offset:20480
	s_waitcnt lgkmcnt(0)
	v_mfma_f32_32x32x16_bf16 v[48:63], v[104:107], v[108:111], v[48:63]
	v_mfma_f32_32x32x16_bf16 v[32:47], v[104:107], v[112:115], v[32:47]
	ds_read_b128 v[104:107], v80 offset:4096
	s_waitcnt lgkmcnt(0)
	v_mfma_f32_32x32x16_bf16 v[16:31], v[104:107], v[108:111], v[16:31]
	v_mfma_f32_32x32x16_bf16 v[0:15], v[104:107], v[112:115], v[0:15]
	ds_read_b128 v[104:107], v82
	ds_read_b128 v[108:111], v85 offset:16384
	ds_read_b128 v[112:115], v85 offset:20480
	s_waitcnt lgkmcnt(0)
	v_mfma_f32_32x32x16_bf16 v[48:63], v[104:107], v[108:111], v[48:63]
	v_mfma_f32_32x32x16_bf16 v[32:47], v[104:107], v[112:115], v[32:47]
	ds_read_b128 v[104:107], v82 offset:4096
	s_waitcnt lgkmcnt(0)
	v_mfma_f32_32x32x16_bf16 v[16:31], v[104:107], v[108:111], v[16:31]
	v_mfma_f32_32x32x16_bf16 v[0:15], v[104:107], v[112:115], v[0:15]
	ds_read_b128 v[104:107], v86
	ds_read_b128 v[108:111], v87 offset:16384
	ds_read_b128 v[112:115], v87 offset:20480
	s_waitcnt lgkmcnt(0)
	v_mfma_f32_32x32x16_bf16 v[48:63], v[104:107], v[108:111], v[48:63]
	v_mfma_f32_32x32x16_bf16 v[32:47], v[104:107], v[112:115], v[32:47]
	ds_read_b128 v[104:107], v86 offset:4096
	s_waitcnt vmcnt(0)
	s_waitcnt vmcnt(0) lgkmcnt(0)
	s_barrier
	v_mfma_f32_32x32x16_bf16 v[16:31], v[104:107], v[108:111], v[16:31]
	v_mfma_f32_32x32x16_bf16 v[0:15], v[104:107], v[112:115], v[0:15]
	v_lshl_add_u64 v[104:105], v[64:65], 0, s[4:5]
	global_load_lds_dwordx4 v[104:105], off
	s_mov_b32 m0, s19
	s_nop 0
	global_load_lds_dwordx4 v76, s[56:57]
	s_mov_b32 m0, s22
	s_nop 0
	global_load_lds_dwordx4 v[96:97], off
	s_mov_b32 m0, s23
	v_lshl_add_u64 v[96:97], v[68:69], 0, s[4:5]
	global_load_lds_dwordx4 v77, s[56:57]
	s_mov_b32 m0, s29
	s_nop 0
	global_load_lds_dwordx4 v[96:97], off
	s_mov_b32 m0, s69
	v_lshl_add_u64 v[96:97], v[70:71], 0, s[4:5]
	global_load_lds_dwordx4 v78, s[56:57]
	s_mov_b32 m0, s70
	s_mov_b64 s[4:5], 0x580
	global_load_lds_dwordx4 v[96:97], off
	s_mov_b32 m0, s71
	v_lshl_add_u64 v[88:89], v[66:67], 0, s[4:5]
	global_load_lds_dwordx4 v84, s[56:57]
	ds_read_b128 v[96:99], v79 offset:32768
	ds_read_b128 v[100:103], v81 offset:49152
	ds_read_b128 v[104:107], v81 offset:53248
	s_waitcnt lgkmcnt(0)
	v_mfma_f32_32x32x16_bf16 v[48:63], v[96:99], v[100:103], v[48:63]
	s_mov_b32 m0, s84
	v_mfma_f32_32x32x16_bf16 v[32:47], v[96:99], v[104:107], v[32:47]
	ds_read_b128 v[96:99], v79 offset:36864
	s_waitcnt lgkmcnt(0)
	v_mfma_f32_32x32x16_bf16 v[16:31], v[96:99], v[100:103], v[16:31]
	v_mfma_f32_32x32x16_bf16 v[0:15], v[96:99], v[104:107], v[0:15]
	ds_read_b128 v[96:99], v80 offset:32768
	ds_read_b128 v[100:103], v83 offset:49152
	ds_read_b128 v[104:107], v83 offset:53248
	s_waitcnt lgkmcnt(0)
	v_mfma_f32_32x32x16_bf16 v[48:63], v[96:99], v[100:103], v[48:63]
	v_mfma_f32_32x32x16_bf16 v[32:47], v[96:99], v[104:107], v[32:47]
	ds_read_b128 v[96:99], v80 offset:36864
	s_waitcnt lgkmcnt(0)
	v_mfma_f32_32x32x16_bf16 v[16:31], v[96:99], v[100:103], v[16:31]
	v_mfma_f32_32x32x16_bf16 v[0:15], v[96:99], v[104:107], v[0:15]
	ds_read_b128 v[96:99], v82 offset:32768
	ds_read_b128 v[100:103], v85 offset:49152
	ds_read_b128 v[104:107], v85 offset:53248
	s_waitcnt lgkmcnt(0)
	v_mfma_f32_32x32x16_bf16 v[48:63], v[96:99], v[100:103], v[48:63]
	v_mfma_f32_32x32x16_bf16 v[32:47], v[96:99], v[104:107], v[32:47]
	ds_read_b128 v[96:99], v82 offset:36864
	s_waitcnt lgkmcnt(0)
	v_mfma_f32_32x32x16_bf16 v[16:31], v[96:99], v[100:103], v[16:31]
	v_mfma_f32_32x32x16_bf16 v[0:15], v[96:99], v[104:107], v[0:15]
	ds_read_b128 v[96:99], v86 offset:32768
	ds_read_b128 v[100:103], v87 offset:49152
	ds_read_b128 v[104:107], v87 offset:53248
	s_waitcnt lgkmcnt(0)
	v_mfma_f32_32x32x16_bf16 v[48:63], v[96:99], v[100:103], v[48:63]
	v_mfma_f32_32x32x16_bf16 v[32:47], v[96:99], v[104:107], v[32:47]
	ds_read_b128 v[96:99], v86 offset:36864
	s_waitcnt vmcnt(0)
	s_waitcnt vmcnt(0) lgkmcnt(0)
	s_barrier
; #define WAIT_V0() asm volatile("s_waitcnt vmcnt(0)" ::: "memory")
; DI void gemm_core(char* smem, int nk, const char* Ab, const char* Bb, const unsigned (&aoff)[4], const unsigned (&boff)[4],
;                   f32x16 (&acc)[2][2]) {
;     ...
;   for (int kt = 0; kt < nk; ++kt) {
;     const int cur = kt & 1;
;     if (kt + 1 < nk) stage(cur ^ 1, kt + 1);
;     const char* sb = smem + cur * STAGE_B;
; #pragma unroll
;     for (int ks = 0; ks < 4; ++ks) {
;       bf16x8 af[2], bfr[2];
; #pragma unroll
;       for (int mb = 0; mb < 2; ++mb) af[mb] = *(const bf16x8*)(sb + a_base + mb * 4096 + xo[ks]);
; #pragma unroll
;       for (int nb = 0; nb < 2; ++nb) bfr[nb] = *(const bf16x8*)(sb + b_base + nb * 4096 + xo[ks]);
; #pragma unroll
;       for (int mb = 0; mb < 2; ++mb)
; #pragma unroll
;         for (int nb = 0; nb < 2; ++nb)
;           acc[mb][nb] = __builtin_amdgcn_mfma_f32_32x32x16_bf16(af[mb], bfr[nb], acc[mb][nb], 0, 0, 0);
;     }
;     WAIT_V0();
;     __syncthreads();
;   }
	v_mfma_f32_32x32x16_bf16 v[16:31], v[96:99], v[100:103], v[16:31]
	v_mfma_f32_32x32x16_bf16 v[0:15], v[96:99], v[104:107], v[0:15]
	v_lshl_add_u64 v[96:97], v[64:65], 0, s[4:5]
	global_load_lds_dwordx4 v[96:97], off
	s_mov_b32 m0, s85
	s_nop 0
	global_load_lds_dwordx4 v76, s[58:59]
	s_mov_b32 m0, s86
	s_nop 0
	global_load_lds_dwordx4 v[88:89], off
	s_mov_b32 m0, s87
	v_lshl_add_u64 v[88:89], v[68:69], 0, s[4:5]
	global_load_lds_dwordx4 v77, s[58:59]
	s_mov_b32 m0, s88
	s_nop 0
	global_load_lds_dwordx4 v[88:89], off
	s_mov_b32 m0, s89
	v_lshl_add_u64 v[88:89], v[70:71], 0, s[4:5]
	global_load_lds_dwordx4 v78, s[58:59]
	s_mov_b32 m0, s90
	s_mov_b64 s[4:5], 0x600
	global_load_lds_dwordx4 v[88:89], off
	s_mov_b32 m0, s91
	s_nop 0
	global_load_lds_dwordx4 v84, s[58:59]
	ds_read_b128 v[88:91], v79
	ds_read_b128 v[92:95], v81 offset:16384
	ds_read_b128 v[96:99], v81 offset:20480
	s_waitcnt lgkmcnt(0)
	v_mfma_f32_32x32x16_bf16 v[48:63], v[88:91], v[92:95], v[48:63]
	s_mov_b32 m0, s18
	v_mfma_f32_32x32x16_bf16 v[32:47], v[88:91], v[96:99], v[32:47]
	ds_read_b128 v[88:91], v79 offset:4096
	s_waitcnt lgkmcnt(0)
	v_mfma_f32_32x32x16_bf16 v[16:31], v[88:91], v[92:95], v[16:31]
	v_mfma_f32_32x32x16_bf16 v[0:15], v[88:91], v[96:99], v[0:15]
	ds_read_b128 v[88:91], v80
	ds_read_b128 v[92:95], v83 offset:16384
	ds_read_b128 v[96:99], v83 offset:20480
	s_waitcnt lgkmcnt(0)
	v_mfma_f32_32x32x16_bf16 v[48:63], v[88:91], v[92:95], v[48:63]
	v_mfma_f32_32x32x16_bf16 v[32:47], v[88:91], v[96:99], v[32:47]
	ds_read_b128 v[88:91], v80 offset:4096
	s_waitcnt lgkmcnt(0)
	v_mfma_f32_32x32x16_bf16 v[16:31], v[88:91], v[92:95], v[16:31]
	v_mfma_f32_32x32x16_bf16 v[0:15], v[88:91], v[96:99], v[0:15]
	ds_read_b128 v[88:91], v82
	ds_read_b128 v[92:95], v85 offset:16384
	ds_read_b128 v[96:99], v85 offset:20480
	s_waitcnt lgkmcnt(0)
	v_mfma_f32_32x32x16_bf16 v[48:63], v[88:91], v[92:95], v[48:63]
	v_mfma_f32_32x32x16_bf16 v[32:47], v[88:91], v[96:99], v[32:47]
	ds_read_b128 v[88:91], v82 offset:4096
	s_waitcnt lgkmcnt(0)
	v_mfma_f32_32x32x16_bf16 v[16:31], v[88:91], v[92:95], v[16:31]
	v_mfma_f32_32x32x16_bf16 v[0:15], v[88:91], v[96:99], v[0:15]
	ds_read_b128 v[88:91], v86
	ds_read_b128 v[92:95], v87 offset:16384
	ds_read_b128 v[96:99], v87 offset:20480
	s_waitcnt lgkmcnt(0)
	v_mfma_f32_32x32x16_bf16 v[48:63], v[88:91], v[92:95], v[48:63]
	v_mfma_f32_32x32x16_bf16 v[32:47], v[88:91], v[96:99], v[32:47]
	ds_read_b128 v[88:91], v86 offset:4096
	s_waitcnt vmcnt(0)
	s_waitcnt vmcnt(0) lgkmcnt(0)
	s_barrier
	v_mfma_f32_32x32x16_bf16 v[16:31], v[88:91], v[92:95], v[16:31]
	v_mfma_f32_32x32x16_bf16 v[0:15], v[88:91], v[96:99], v[0:15]
	v_lshl_add_u64 v[88:89], v[64:65], 0, s[4:5]
	global_load_lds_dwordx4 v[88:89], off
	s_mov_b32 m0, s19
	v_lshl_add_u64 v[88:89], v[66:67], 0, s[4:5]
	global_load_lds_dwordx4 v76, s[60:61]
	s_mov_b32 m0, s22
	s_nop 0
	global_load_lds_dwordx4 v[88:89], off
	s_mov_b32 m0, s23
	v_lshl_add_u64 v[88:89], v[68:69], 0, s[4:5]
	global_load_lds_dwordx4 v77, s[60:61]
	s_mov_b32 m0, s29
	s_nop 0
	global_load_lds_dwordx4 v[88:89], off
	s_mov_b32 m0, s69
	v_lshl_add_u64 v[88:89], v[70:71], 0, s[4:5]
	global_load_lds_dwordx4 v78, s[60:61]
	s_mov_b32 m0, s70
	s_mov_b64 s[4:5], 0x680
	global_load_lds_dwordx4 v[88:89], off
	s_mov_b32 m0, s71
	s_nop 0
	global_load_lds_dwordx4 v84, s[60:61]
	ds_read_b128 v[88:91], v79 offset:32768
	ds_read_b128 v[92:95], v81 offset:49152
	ds_read_b128 v[96:99], v81 offset:53248
	s_waitcnt lgkmcnt(0)
	v_mfma_f32_32x32x16_bf16 v[48:63], v[88:91], v[92:95], v[48:63]
	s_mov_b32 m0, s84
	v_mfma_f32_32x32x16_bf16 v[32:47], v[88:91], v[96:99], v[32:47]
	ds_read_b128 v[88:91], v79 offset:36864
	s_waitcnt lgkmcnt(0)
	v_mfma_f32_32x32x16_bf16 v[16:31], v[88:91], v[92:95], v[16:31]
	v_mfma_f32_32x32x16_bf16 v[0:15], v[88:91], v[96:99], v[0:15]
	ds_read_b128 v[88:91], v80 offset:32768
	ds_read_b128 v[92:95], v83 offset:49152
	ds_read_b128 v[96:99], v83 offset:53248
	s_waitcnt lgkmcnt(0)
	v_mfma_f32_32x32x16_bf16 v[48:63], v[88:91], v[92:95], v[48:63]
	v_mfma_f32_32x32x16_bf16 v[32:47], v[88:91], v[96:99], v[32:47]
	ds_read_b128 v[88:91], v80 offset:36864
	s_waitcnt lgkmcnt(0)
	v_mfma_f32_32x32x16_bf16 v[16:31], v[88:91], v[92:95], v[16:31]
	v_mfma_f32_32x32x16_bf16 v[0:15], v[88:91], v[96:99], v[0:15]
	ds_read_b128 v[88:91], v82 offset:32768
	ds_read_b128 v[92:95], v85 offset:49152
	ds_read_b128 v[96:99], v85 offset:53248
	s_waitcnt lgkmcnt(0)
	v_mfma_f32_32x32x16_bf16 v[48:63], v[88:91], v[92:95], v[48:63]
	v_mfma_f32_32x32x16_bf16 v[32:47], v[88:91], v[96:99], v[32:47]
	ds_read_b128 v[88:91], v82 offset:36864
	s_waitcnt lgkmcnt(0)
	v_mfma_f32_32x32x16_bf16 v[16:31], v[88:91], v[92:95], v[16:31]
	v_mfma_f32_32x32x16_bf16 v[0:15], v[88:91], v[96:99], v[0:15]
	ds_read_b128 v[88:91], v86 offset:32768
	ds_read_b128 v[92:95], v87 offset:49152
	ds_read_b128 v[96:99], v87 offset:53248
	s_waitcnt lgkmcnt(0)
	v_mfma_f32_32x32x16_bf16 v[48:63], v[88:91], v[92:95], v[48:63]
	v_mfma_f32_32x32x16_bf16 v[32:47], v[88:91], v[96:99], v[32:47]
	ds_read_b128 v[88:91], v86 offset:36864
	s_waitcnt vmcnt(0)
	s_waitcnt vmcnt(0) lgkmcnt(0)
	s_barrier
; #define WAIT_V0() asm volatile("s_waitcnt vmcnt(0)" ::: "memory")
; DI void gemm_core(char* smem, int nk, const char* Ab, const char* Bb, const unsigned (&aoff)[4], const unsigned (&boff)[4],
;                   f32x16 (&acc)[2][2]) {
;     ...
;   for (int kt = 0; kt < nk; ++kt) {
;     const int cur = kt & 1;
;     if (kt + 1 < nk) stage(cur ^ 1, kt + 1);
;     const char* sb = smem + cur * STAGE_B;
; #pragma unroll
;     for (int ks = 0; ks < 4; ++ks) {
;       bf16x8 af[2], bfr[2];
; #pragma unroll
;       for (int mb = 0; mb < 2; ++mb) af[mb] = *(const bf16x8*)(sb + a_base + mb * 4096 + xo[ks]);
; #pragma unroll
;       for (int nb = 0; nb < 2; ++nb) bfr[nb] = *(const bf16x8*)(sb + b_base + nb * 4096 + xo[ks]);
; #pragma unroll
;       for (int mb = 0; mb < 2; ++mb)
; #pragma unroll
;         for (int nb = 0; nb < 2; ++nb)
;           acc[mb][nb] = __builtin_amdgcn_mfma_f32_32x32x16_bf16(af[mb], bfr[nb], acc[mb][nb], 0, 0, 0);
;     }
;     WAIT_V0();
;     __syncthreads();
;   }
	v_mfma_f32_32x32x16_bf16 v[16:31], v[88:91], v[92:95], v[16:31]
	v_mfma_f32_32x32x16_bf16 v[0:15], v[88:91], v[96:99], v[0:15]
	v_lshl_add_u64 v[88:89], v[64:65], 0, s[4:5]
	global_load_lds_dwordx4 v[88:89], off
	s_mov_b32 m0, s85
	v_lshl_add_u64 v[88:89], v[66:67], 0, s[4:5]
	global_load_lds_dwordx4 v76, s[62:63]
	s_mov_b32 m0, s86
	s_nop 0
	global_load_lds_dwordx4 v[88:89], off
	s_mov_b32 m0, s87
	v_lshl_add_u64 v[88:89], v[68:69], 0, s[4:5]
	global_load_lds_dwordx4 v77, s[62:63]
	s_mov_b32 m0, s88
	s_nop 0
	global_load_lds_dwordx4 v[88:89], off
	s_mov_b32 m0, s89
	v_lshl_add_u64 v[88:89], v[70:71], 0, s[4:5]
	global_load_lds_dwordx4 v78, s[62:63]
	s_mov_b32 m0, s90
	s_mov_b64 s[4:5], 0x700
	global_load_lds_dwordx4 v[88:89], off
	s_mov_b32 m0, s91
	s_nop 0
	global_load_lds_dwordx4 v84, s[62:63]
	ds_read_b128 v[88:91], v79
	ds_read_b128 v[92:95], v81 offset:16384
	ds_read_b128 v[96:99], v81 offset:20480
	s_waitcnt lgkmcnt(0)
	v_mfma_f32_32x32x16_bf16 v[48:63], v[88:91], v[92:95], v[48:63]
	s_mov_b32 m0, s18
	v_mfma_f32_32x32x16_bf16 v[32:47], v[88:91], v[96:99], v[32:47]
	ds_read_b128 v[88:91], v79 offset:4096
	s_waitcnt lgkmcnt(0)
	v_mfma_f32_32x32x16_bf16 v[16:31], v[88:91], v[92:95], v[16:31]
	v_mfma_f32_32x32x16_bf16 v[0:15], v[88:91], v[96:99], v[0:15]
	ds_read_b128 v[88:91], v80
	ds_read_b128 v[92:95], v83 offset:16384
	ds_read_b128 v[96:99], v83 offset:20480
	s_waitcnt lgkmcnt(0)
	v_mfma_f32_32x32x16_bf16 v[48:63], v[88:91], v[92:95], v[48:63]
	v_mfma_f32_32x32x16_bf16 v[32:47], v[88:91], v[96:99], v[32:47]
	ds_read_b128 v[88:91], v80 offset:4096
	s_waitcnt lgkmcnt(0)
	v_mfma_f32_32x32x16_bf16 v[16:31], v[88:91], v[92:95], v[16:31]
	v_mfma_f32_32x32x16_bf16 v[0:15], v[88:91], v[96:99], v[0:15]
	ds_read_b128 v[88:91], v82
	ds_read_b128 v[92:95], v85 offset:16384
	ds_read_b128 v[96:99], v85 offset:20480
	s_waitcnt lgkmcnt(0)
	v_mfma_f32_32x32x16_bf16 v[48:63], v[88:91], v[92:95], v[48:63]
	v_mfma_f32_32x32x16_bf16 v[32:47], v[88:91], v[96:99], v[32:47]
	ds_read_b128 v[88:91], v82 offset:4096
	s_waitcnt lgkmcnt(0)
	v_mfma_f32_32x32x16_bf16 v[16:31], v[88:91], v[92:95], v[16:31]
	v_mfma_f32_32x32x16_bf16 v[0:15], v[88:91], v[96:99], v[0:15]
	ds_read_b128 v[88:91], v86
	ds_read_b128 v[92:95], v87 offset:16384
	ds_read_b128 v[96:99], v87 offset:20480
	s_waitcnt lgkmcnt(0)
	v_mfma_f32_32x32x16_bf16 v[48:63], v[88:91], v[92:95], v[48:63]
	v_mfma_f32_32x32x16_bf16 v[32:47], v[88:91], v[96:99], v[32:47]
	ds_read_b128 v[88:91], v86 offset:4096
	s_waitcnt vmcnt(0)
	s_waitcnt vmcnt(0) lgkmcnt(0)
	s_barrier
	v_mfma_f32_32x32x16_bf16 v[16:31], v[88:91], v[92:95], v[16:31]
	v_mfma_f32_32x32x16_bf16 v[0:15], v[88:91], v[96:99], v[0:15]
	v_lshl_add_u64 v[88:89], v[64:65], 0, s[4:5]
	global_load_lds_dwordx4 v[88:89], off
	s_mov_b32 m0, s19
	v_lshl_add_u64 v[88:89], v[66:67], 0, s[4:5]
	global_load_lds_dwordx4 v76, s[64:65]
	s_mov_b32 m0, s22
	s_nop 0
	global_load_lds_dwordx4 v[88:89], off
	s_mov_b32 m0, s23
	v_lshl_add_u64 v[88:89], v[68:69], 0, s[4:5]
	global_load_lds_dwordx4 v77, s[64:65]
	s_mov_b32 m0, s29
	s_nop 0
	global_load_lds_dwordx4 v[88:89], off
	s_mov_b32 m0, s69
	v_lshl_add_u64 v[88:89], v[70:71], 0, s[4:5]
	global_load_lds_dwordx4 v78, s[64:65]
	s_mov_b32 m0, s70
	s_mov_b64 s[4:5], 0x780
	global_load_lds_dwordx4 v[88:89], off
	s_mov_b32 m0, s71
	v_lshl_add_u64 v[64:65], v[64:65], 0, s[4:5]
	global_load_lds_dwordx4 v84, s[64:65]
	ds_read_b128 v[88:91], v79 offset:32768
	ds_read_b128 v[92:95], v81 offset:49152
	ds_read_b128 v[96:99], v81 offset:53248
	s_waitcnt lgkmcnt(0)
	v_mfma_f32_32x32x16_bf16 v[48:63], v[88:91], v[92:95], v[48:63]
	s_mov_b32 m0, s84
	s_movk_i32 s4, 0x4000
	v_mfma_f32_32x32x16_bf16 v[32:47], v[88:91], v[96:99], v[32:47]
	ds_read_b128 v[88:91], v79 offset:36864
	s_waitcnt lgkmcnt(0)
	v_mfma_f32_32x32x16_bf16 v[16:31], v[88:91], v[92:95], v[16:31]
	v_mfma_f32_32x32x16_bf16 v[0:15], v[88:91], v[96:99], v[0:15]
	ds_read_b128 v[88:91], v80 offset:32768
	ds_read_b128 v[92:95], v83 offset:49152
	ds_read_b128 v[96:99], v83 offset:53248
	s_waitcnt lgkmcnt(0)
	v_mfma_f32_32x32x16_bf16 v[48:63], v[88:91], v[92:95], v[48:63]
	v_mfma_f32_32x32x16_bf16 v[32:47], v[88:91], v[96:99], v[32:47]
	ds_read_b128 v[88:91], v80 offset:36864
	s_waitcnt lgkmcnt(0)
	v_mfma_f32_32x32x16_bf16 v[16:31], v[88:91], v[92:95], v[16:31]
	v_mfma_f32_32x32x16_bf16 v[0:15], v[88:91], v[96:99], v[0:15]
	ds_read_b128 v[88:91], v82 offset:32768
	ds_read_b128 v[92:95], v85 offset:49152
	ds_read_b128 v[96:99], v85 offset:53248
	s_waitcnt lgkmcnt(0)
	v_mfma_f32_32x32x16_bf16 v[48:63], v[88:91], v[92:95], v[48:63]
	v_mfma_f32_32x32x16_bf16 v[32:47], v[88:91], v[96:99], v[32:47]
	ds_read_b128 v[88:91], v82 offset:36864
	s_waitcnt lgkmcnt(0)
	v_mfma_f32_32x32x16_bf16 v[16:31], v[88:91], v[92:95], v[16:31]
	v_mfma_f32_32x32x16_bf16 v[0:15], v[88:91], v[96:99], v[0:15]
	ds_read_b128 v[88:91], v86 offset:32768
	ds_read_b128 v[92:95], v87 offset:49152
	ds_read_b128 v[96:99], v87 offset:53248
	s_waitcnt lgkmcnt(0)
	v_mfma_f32_32x32x16_bf16 v[48:63], v[88:91], v[92:95], v[48:63]
	v_mfma_f32_32x32x16_bf16 v[32:47], v[88:91], v[96:99], v[32:47]
	ds_read_b128 v[88:91], v86 offset:36864
	s_waitcnt vmcnt(0)
	s_waitcnt vmcnt(0) lgkmcnt(0)
	s_barrier
; #define WAIT_V0() asm volatile("s_waitcnt vmcnt(0)" ::: "memory")
; DI void gemm_core(char* smem, int nk, const char* Ab, const char* Bb, const unsigned (&aoff)[4], const unsigned (&boff)[4],
;                   f32x16 (&acc)[2][2]) {
;     ...
;   for (int kt = 0; kt < nk; ++kt) {
;     const int cur = kt & 1;
;     if (kt + 1 < nk) stage(cur ^ 1, kt + 1);
;     const char* sb = smem + cur * STAGE_B;
; #pragma unroll
;     for (int ks = 0; ks < 4; ++ks) {
;       bf16x8 af[2], bfr[2];
; #pragma unroll
;       for (int mb = 0; mb < 2; ++mb) af[mb] = *(const bf16x8*)(sb + a_base + mb * 4096 + xo[ks]);
; #pragma unroll
;       for (int nb = 0; nb < 2; ++nb) bfr[nb] = *(const bf16x8*)(sb + b_base + nb * 4096 + xo[ks]);
; #pragma unroll
;       for (int mb = 0; mb < 2; ++mb)
; #pragma unroll
;         for (int nb = 0; nb < 2; ++nb)
;           acc[mb][nb] = __builtin_amdgcn_mfma_f32_32x32x16_bf16(af[mb], bfr[nb], acc[mb][nb], 0, 0, 0);
;     }
;     WAIT_V0();
;     __syncthreads();
;   }
	global_load_lds_dwordx4 v[64:65], off
	s_mov_b32 m0, s85
	v_lshl_add_u64 v[64:65], v[66:67], 0, s[6:7]
	global_load_lds_dwordx4 v76, s[66:67]
	s_mov_b32 m0, s86
	v_mfma_f32_32x32x16_bf16 v[16:31], v[88:91], v[92:95], v[16:31]
	global_load_lds_dwordx4 v[64:65], off
	s_mov_b32 m0, s87
	v_lshl_add_u64 v[64:65], v[68:69], 0, s[6:7]
	global_load_lds_dwordx4 v77, s[66:67]
	s_mov_b32 m0, s88
	v_mfma_f32_32x32x16_bf16 v[0:15], v[88:91], v[96:99], v[0:15]
	global_load_lds_dwordx4 v[64:65], off
	s_mov_b32 m0, s89
	v_lshl_add_u64 v[64:65], v[70:71], 0, s[6:7]
	global_load_lds_dwordx4 v78, s[66:67]
	s_mov_b32 m0, s90
	v_readlane_b32 s86, v254, 58
	global_load_lds_dwordx4 v[64:65], off
	s_mov_b32 m0, s91
	v_readlane_b32 s87, v254, 59
	global_load_lds_dwordx4 v84, s[66:67]
	ds_read_b128 v[64:67], v79
	ds_read_b128 v[68:71], v81 offset:16384
	ds_read_b128 v[88:91], v81 offset:20480
	s_waitcnt lgkmcnt(0)
	v_mfma_f32_32x32x16_bf16 v[48:63], v[64:67], v[68:71], v[48:63]
	v_mfma_f32_32x32x16_bf16 v[32:47], v[64:67], v[88:91], v[32:47]
	ds_read_b128 v[64:67], v79 offset:4096
	s_waitcnt lgkmcnt(0)
	v_mfma_f32_32x32x16_bf16 v[16:31], v[64:67], v[68:71], v[16:31]
	v_mfma_f32_32x32x16_bf16 v[0:15], v[64:67], v[88:91], v[0:15]
	ds_read_b128 v[64:67], v80
	ds_read_b128 v[68:71], v83 offset:16384
	ds_read_b128 v[88:91], v83 offset:20480
	s_waitcnt lgkmcnt(0)
	v_mfma_f32_32x32x16_bf16 v[48:63], v[64:67], v[68:71], v[48:63]
	v_mfma_f32_32x32x16_bf16 v[32:47], v[64:67], v[88:91], v[32:47]
	ds_read_b128 v[64:67], v80 offset:4096
	s_waitcnt lgkmcnt(0)
	v_mfma_f32_32x32x16_bf16 v[16:31], v[64:67], v[68:71], v[16:31]
	v_mfma_f32_32x32x16_bf16 v[0:15], v[64:67], v[88:91], v[0:15]
	ds_read_b128 v[64:67], v82
	ds_read_b128 v[68:71], v85 offset:16384
	ds_read_b128 v[88:91], v85 offset:20480
	s_waitcnt lgkmcnt(0)
	v_mfma_f32_32x32x16_bf16 v[48:63], v[64:67], v[68:71], v[48:63]
	v_mfma_f32_32x32x16_bf16 v[32:47], v[64:67], v[88:91], v[32:47]
	ds_read_b128 v[64:67], v82 offset:4096
	s_waitcnt lgkmcnt(0)
	v_mfma_f32_32x32x16_bf16 v[16:31], v[64:67], v[68:71], v[16:31]
	v_mfma_f32_32x32x16_bf16 v[0:15], v[64:67], v[88:91], v[0:15]
	ds_read_b128 v[64:67], v86
	ds_read_b128 v[68:71], v87 offset:16384
	ds_read_b128 v[88:91], v87 offset:20480
	s_waitcnt lgkmcnt(0)
	v_mfma_f32_32x32x16_bf16 v[48:63], v[64:67], v[68:71], v[48:63]
	v_mfma_f32_32x32x16_bf16 v[32:47], v[64:67], v[88:91], v[32:47]
	ds_read_b128 v[64:67], v86 offset:4096
	s_waitcnt vmcnt(0)
	s_waitcnt vmcnt(0) lgkmcnt(0)
	s_barrier
	v_mfma_f32_32x32x16_bf16 v[16:31], v[64:67], v[68:71], v[16:31]
	v_mfma_f32_32x32x16_bf16 v[0:15], v[64:67], v[88:91], v[0:15]
	ds_read_b128 v[64:67], v79 offset:32768
	ds_read_b128 v[68:71], v81 offset:49152
	ds_read_b128 v[88:91], v81 offset:53248
	s_waitcnt lgkmcnt(1)
	v_mfma_f32_32x32x16_bf16 v[48:63], v[64:67], v[68:71], v[48:63]
	s_waitcnt lgkmcnt(0)
	v_mfma_f32_32x32x16_bf16 v[32:47], v[64:67], v[88:91], v[32:47]
	ds_read_b128 v[64:67], v79 offset:36864
	s_waitcnt lgkmcnt(0)
	v_mfma_f32_32x32x16_bf16 v[16:31], v[64:67], v[68:71], v[16:31]
	v_mfma_f32_32x32x16_bf16 v[0:15], v[64:67], v[88:91], v[0:15]
	ds_read_b128 v[64:67], v80 offset:32768
	ds_read_b128 v[68:71], v83 offset:49152
	ds_read_b128 v[76:79], v83 offset:53248
	s_waitcnt lgkmcnt(1)
	v_mfma_f32_32x32x16_bf16 v[48:63], v[64:67], v[68:71], v[48:63]
	s_waitcnt lgkmcnt(0)
	v_mfma_f32_32x32x16_bf16 v[32:47], v[64:67], v[76:79], v[32:47]
	ds_read_b128 v[64:67], v80 offset:36864
	s_waitcnt lgkmcnt(0)
	v_mfma_f32_32x32x16_bf16 v[16:31], v[64:67], v[68:71], v[16:31]
	v_mfma_f32_32x32x16_bf16 v[0:15], v[64:67], v[76:79], v[0:15]
	ds_read_b128 v[64:67], v82 offset:32768
	ds_read_b128 v[68:71], v85 offset:49152
	ds_read_b128 v[76:79], v85 offset:53248
	s_waitcnt lgkmcnt(1)
	v_mfma_f32_32x32x16_bf16 v[48:63], v[64:67], v[68:71], v[48:63]
	s_waitcnt lgkmcnt(0)
	v_mfma_f32_32x32x16_bf16 v[32:47], v[64:67], v[76:79], v[32:47]
	ds_read_b128 v[64:67], v82 offset:36864
	s_waitcnt lgkmcnt(0)
	v_mfma_f32_32x32x16_bf16 v[16:31], v[64:67], v[68:71], v[16:31]
	ds_read_b128 v[68:71], v87 offset:53248
	ds_read_b128 v[80:83], v87 offset:49152
	ds_read_b128 v[88:91], v86 offset:36864
	ds_read_b128 v[84:87], v86 offset:32768
	s_waitcnt vmcnt(0)
	s_waitcnt lgkmcnt(0)
	s_barrier
; template <class F>
; DI void epi_foreach(const f32x16 (&acc)[2][2], F f) {
;     ...
;   for (int mb = 0; mb < 2; ++mb)
; #pragma unroll
;     for (int nb = 0; nb < 2; ++nb)
; #pragma unroll
;       for (int r = 0; r < 16; ++r) {
;         const int row = wm * 64 + mb * 32 + (r & 3) + 8 * (r >> 2) + 4 * (lane >> 5);
;         const int col = wn * 64 + nb * 32 + (lane & 31);
;         f(row, col, acc[mb][nb][r]);
;         if ((r & 7) == 7) __builtin_amdgcn_sched_barrier(0);
; DI void phase_up(const Params& P, int layer, char* smem) {
;     ...
;     epi_foreach(acc, [&](int row, int col, float v) __attribute__((always_inline)) { Cs[row * 136 + col] = f2bf(v); });
;     __syncthreads();
;     {
;       const int col = tid & 63, rb = tid >> 6;
;       const int cv = nt * 64 + col, cg_ = DFF + nt * 64 + col;
;       const float w0v = cw[cv], w1v = cw[5632 + cv], w2v = cw[2 * 5632 + cv], bv = cb[cv];
;       const float w0g = cw[cg_], w1g = cw[5632 + cg_], w2g = cw[2 * 5632 + cg_], bgt = cb[cg_];
	v_mfma_f32_32x32x16_bf16 v[48:63], v[84:87], v[80:83], v[48:63]
	v_mfma_f32_32x32x16_bf16 v[0:15], v[64:67], v[76:79], v[0:15]
	v_mov_b32_e32 v64, v161
	v_mov_b32_e32 v65, v161
	v_lshrrev_b32_e32 v67, 3, v64
	v_and_b32_e32 v67, 4, v67
	v_lshrrev_b32_e32 v66, 1, v65
	v_and_b32_e32 v64, 31, v64
	v_and_or_b32 v64, v65, 64, v64
	v_and_or_b32 v65, v66, s3, v67
	v_mul_lo_u32 v65, v65, s97
	s_nop 1
	v_cvt_pk_bf16_f32 v48, v48, s0
	v_lshl_add_u32 v64, v64, 1, v65
	ds_write_b16 v64, v48
	v_cvt_pk_bf16_f32 v48, v49, s0
	ds_write_b16 v64, v48 offset:272
	v_cvt_pk_bf16_f32 v48, v50, s0
	ds_write_b16 v64, v48 offset:544
	v_cvt_pk_bf16_f32 v48, v51, s0
	ds_write_b16 v64, v48 offset:816
	v_cvt_pk_bf16_f32 v48, v52, s0
	ds_write_b16 v64, v48 offset:2176
	v_cvt_pk_bf16_f32 v48, v53, s0
	ds_write_b16 v64, v48 offset:2448
	v_cvt_pk_bf16_f32 v48, v54, s0
	ds_write_b16 v64, v48 offset:2720
	v_cvt_pk_bf16_f32 v48, v55, s0
	v_mfma_f32_32x32x16_bf16 v[32:47], v[84:87], v[68:71], v[32:47]
	ds_write_b16 v64, v48 offset:2992
	v_mfma_f32_32x32x16_bf16 v[16:31], v[88:91], v[80:83], v[16:31]
	v_mfma_f32_32x32x16_bf16 v[0:15], v[88:91], v[68:71], v[0:15]
	v_cvt_pk_bf16_f32 v48, v56, s0
	ds_write_b16 v64, v48 offset:4352
	v_cvt_pk_bf16_f32 v48, v57, s0
	ds_write_b16 v64, v48 offset:4624
	v_cvt_pk_bf16_f32 v48, v58, s0
	ds_write_b16 v64, v48 offset:4896
	v_cvt_pk_bf16_f32 v48, v59, s0
	ds_write_b16 v64, v48 offset:5168
	v_cvt_pk_bf16_f32 v48, v60, s0
	ds_write_b16 v64, v48 offset:6528
	v_cvt_pk_bf16_f32 v48, v61, s0
	ds_write_b16 v64, v48 offset:6800
	v_cvt_pk_bf16_f32 v48, v62, s0
	ds_write_b16 v64, v48 offset:7072
	v_cvt_pk_bf16_f32 v48, v63, s0
	ds_write_b16 v64, v48 offset:7344
	v_cvt_pk_bf16_f32 v32, v32, s0
	ds_write_b16 v64, v32 offset:64
	v_cvt_pk_bf16_f32 v32, v33, s0
	ds_write_b16 v64, v32 offset:336
	v_cvt_pk_bf16_f32 v32, v34, s0
	ds_write_b16 v64, v32 offset:608
	v_cvt_pk_bf16_f32 v32, v35, s0
	ds_write_b16 v64, v32 offset:880
	v_cvt_pk_bf16_f32 v32, v36, s0
	ds_write_b16 v64, v32 offset:2240
	v_cvt_pk_bf16_f32 v32, v37, s0
	ds_write_b16 v64, v32 offset:2512
	v_cvt_pk_bf16_f32 v32, v38, s0
	ds_write_b16 v64, v32 offset:2784
	v_cvt_pk_bf16_f32 v32, v39, s0
	ds_write_b16 v64, v32 offset:3056
	v_cvt_pk_bf16_f32 v32, v40, s0
	ds_write_b16 v64, v32 offset:4416
	v_cvt_pk_bf16_f32 v32, v41, s0
	ds_write_b16 v64, v32 offset:4688
	v_cvt_pk_bf16_f32 v32, v42, s0
	ds_write_b16 v64, v32 offset:4960
	v_cvt_pk_bf16_f32 v32, v43, s0
	ds_write_b16 v64, v32 offset:5232
	v_cvt_pk_bf16_f32 v32, v44, s0
	ds_write_b16 v64, v32 offset:6592
	v_cvt_pk_bf16_f32 v32, v45, s0
	ds_write_b16 v64, v32 offset:6864
	v_cvt_pk_bf16_f32 v32, v46, s0
	ds_write_b16 v64, v32 offset:7136
	v_cvt_pk_bf16_f32 v32, v47, s0
	ds_write_b16 v64, v32 offset:7408
	v_cvt_pk_bf16_f32 v16, v16, s0
	ds_write_b16 v64, v16 offset:8704
	v_cvt_pk_bf16_f32 v16, v17, s0
	ds_write_b16 v64, v16 offset:8976
	v_cvt_pk_bf16_f32 v16, v18, s0
	ds_write_b16 v64, v16 offset:9248
	v_cvt_pk_bf16_f32 v16, v19, s0
	ds_write_b16 v64, v16 offset:9520
	v_cvt_pk_bf16_f32 v16, v20, s0
	ds_write_b16 v64, v16 offset:10880
	v_cvt_pk_bf16_f32 v16, v21, s0
	ds_write_b16 v64, v16 offset:11152
	v_cvt_pk_bf16_f32 v16, v22, s0
	ds_write_b16 v64, v16 offset:11424
	v_cvt_pk_bf16_f32 v16, v23, s0
	ds_write_b16 v64, v16 offset:11696
	v_cvt_pk_bf16_f32 v16, v24, s0
	ds_write_b16 v64, v16 offset:13056
	v_cvt_pk_bf16_f32 v16, v25, s0
	ds_write_b16 v64, v16 offset:13328
	v_cvt_pk_bf16_f32 v16, v26, s0
	ds_write_b16 v64, v16 offset:13600
	v_cvt_pk_bf16_f32 v16, v27, s0
	ds_write_b16 v64, v16 offset:13872
	v_cvt_pk_bf16_f32 v16, v28, s0
	ds_write_b16 v64, v16 offset:15232
	v_cvt_pk_bf16_f32 v16, v29, s0
	ds_write_b16 v64, v16 offset:15504
	v_cvt_pk_bf16_f32 v16, v30, s0
	ds_write_b16 v64, v16 offset:15776
	v_cvt_pk_bf16_f32 v16, v31, s0
	ds_write_b16 v64, v16 offset:16048
	v_cvt_pk_bf16_f32 v0, v0, s0
	ds_write_b16 v64, v0 offset:8768
	v_cvt_pk_bf16_f32 v0, v1, s0
	ds_write_b16 v64, v0 offset:9040
	v_cvt_pk_bf16_f32 v0, v2, s0
	ds_write_b16 v64, v0 offset:9312
	v_cvt_pk_bf16_f32 v0, v3, s0
	ds_write_b16 v64, v0 offset:9584
	v_cvt_pk_bf16_f32 v0, v4, s0
	ds_write_b16 v64, v0 offset:10944
	v_cvt_pk_bf16_f32 v0, v5, s0
	ds_write_b16 v64, v0 offset:11216
	v_cvt_pk_bf16_f32 v0, v6, s0
	ds_write_b16 v64, v0 offset:11488
	v_cvt_pk_bf16_f32 v0, v7, s0
	ds_write_b16 v64, v0 offset:11760
	v_cvt_pk_bf16_f32 v0, v8, s0
	ds_write_b16 v64, v0 offset:13120
	v_cvt_pk_bf16_f32 v0, v9, s0
	ds_write_b16 v64, v0 offset:13392
	v_cvt_pk_bf16_f32 v0, v10, s0
	ds_write_b16 v64, v0 offset:13664
	v_cvt_pk_bf16_f32 v0, v11, s0
	ds_write_b16 v64, v0 offset:13936
	v_cvt_pk_bf16_f32 v0, v12, s0
	ds_write_b16 v64, v0 offset:15296
	v_cvt_pk_bf16_f32 v0, v13, s0
	ds_write_b16 v64, v0 offset:15568
	v_cvt_pk_bf16_f32 v0, v14, s0
	ds_write_b16 v64, v0 offset:15840
	v_cvt_pk_bf16_f32 v0, v15, s0
	ds_write_b16 v64, v0 offset:16112
	s_waitcnt lgkmcnt(0)
	s_barrier
	s_and_saveexec_b64 s[18:19], s[40:41]
	s_mov_b32 s3, 0xb000
	s_cbranch_execz .LBB0_24
	v_add_u32_e32 v136, s21, v74
	v_lshlrev_b64 v[4:5], 2, v[136:137]
	v_lshl_add_u64 v[8:9], s[10:11], 0, v[4:5]
	v_or_b32_e32 v10, s21, v72
	v_lshlrev_b32_e32 v126, 1, v10
	v_lshl_add_u64 v[2:3], s[12:13], 0, v[4:5]
	v_add_co_u32_e32 v4, vcc, 0xb000, v8
	v_ashrrev_i32_e32 v11, 31, v10
	s_nop 0
	v_addc_co_u32_e32 v5, vcc, 0, v9, vcc
	v_lshl_add_u64 v[0:1], v[10:11], 1, s[86:87]
	v_add_co_u32_e32 v6, vcc, 0x5000, v8
	v_lshlrev_b64 v[10:11], 2, v[10:11]
	s_nop 0
	v_addc_co_u32_e32 v7, vcc, 0, v9, vcc
	v_lshl_add_u64 v[12:13], s[12:13], 0, v[10:11]
	v_lshl_add_u64 v[10:11], s[10:11], 0, v[10:11]
	global_load_dword v3, v[2:3], off
	s_mulk_i32 s20, 0x7e
	global_load_dword v5, v[4:5], off
	s_nop 0
	global_load_dword v7, v[6:7], off offset:2048
	s_nop 0
	global_load_dword v9, v[8:9], off
	s_mul_i32 s21, s68, 0x7a
	global_load_dword v2, v[12:13], off
	v_add_co_u32_e32 v12, vcc, s3, v10
	s_sub_i32 s29, s20, s21
	s_nop 0
	v_addc_co_u32_e32 v13, vcc, 0, v11, vcc
	global_load_dword v4, v[12:13], off
	v_add_co_u32_e32 v12, vcc, 0x5000, v10
	s_mov_b64 s[20:21], 0
	s_nop 0
	v_addc_co_u32_e32 v13, vcc, 0, v11, vcc
	global_load_dword v6, v[12:13], off offset:2048
	global_load_dword v8, v[10:11], off
	v_mov_b32_e32 v11, v73
	v_mul_u32_u24_e32 v10, 0x110, v73
	s_waitcnt vmcnt(0)
	v_readfirstlane_b32 s22, v73
	v_add_u32_e32 v10, v75, v10
	v_add_u32_e32 v127, 0x1600, v126
	s_lshl_b32 s22, s22, 1
	s_add_i32 s23, s29, s22
	s_mul_hi_i32 s21, s23, 0x1600
	s_mul_i32 s20, s23, 0x1600
	s_add_u32 s20, s20, s86
	s_addc_u32 s21, s21, s87
	s_branch .LBB0_28
; DI float bf2f(unsigned short u) { return __uint_as_float(((unsigned)u) << 16); }
; DI void phase_up(const Params& P, int layer, char* smem) {
;     ...
;       for (int r = 2 + rb; r < 128; r += 4) {
;         const int tb = tb0 + r;
;         if (tb < S_) {
;           const float val = bv + w0v * bf2f(Cs[(r - 2) * 136 + col]) + w1v * bf2f(Cs[(r - 1) * 136 + col]) + w2v * bf2f(Cs[r * 136 + col]);
;           const float gat = bgt + w0g * bf2f(Cs[(r - 2) * 136 + 64 + col]) + w1g * bf2f(Cs[(r - 1) * 136 + 64 + col]) + w2g * bf2f(Cs[r * 136 + 64 + col]);
;           const float a = gat / (1.f + __expf(-gat)) * val;
;           ACT[(size_t)(b * S_ + tb) * DFF + cv] = f2bf(a);
;         }
;       }
.LBB0_28:
	ds_read_u16 v12, v10
	ds_read_u16 v13, v10 offset:128
	ds_read_u16 v14, v10 offset:272
	ds_read_u16 v15, v10 offset:400
	ds_read_u16 v16, v10 offset:544
	ds_read_u16 v17, v10 offset:672
	ds_read_u16 v18, v10 offset:816
	ds_read_u16 v19, v10 offset:944
	s_waitcnt lgkmcnt(6)
	v_lshlrev_b32_e32 v13, 16, v13
	v_lshlrev_b32_e32 v12, 16, v12
	v_pk_fma_f32 v[118:119], v[8:9], v[12:13], v[2:3]
	s_waitcnt lgkmcnt(4)
	v_lshlrev_b32_e32 v15, 16, v15
	v_lshlrev_b32_e32 v14, 16, v14
	v_pk_fma_f32 v[118:119], v[6:7], v[14:15], v[118:119]
	v_pk_fma_f32 v[120:121], v[8:9], v[14:15], v[2:3]
	s_waitcnt lgkmcnt(2)
	v_lshlrev_b32_e32 v17, 16, v17
	v_lshlrev_b32_e32 v16, 16, v16
	v_pk_fma_f32 v[118:119], v[4:5], v[16:17], v[118:119]
	v_pk_fma_f32 v[120:121], v[6:7], v[16:17], v[120:121]
	s_waitcnt lgkmcnt(0)
	v_lshlrev_b32_e32 v19, 16, v19
	v_lshlrev_b32_e32 v18, 16, v18
	v_mul_f32_e32 v12, 0xbfb8aa3b, v119
	v_pk_fma_f32 v[120:121], v[4:5], v[18:19], v[120:121]
	v_exp_f32_e32 v12, v12
	s_nop 0
	v_mul_f32_e32 v18, 0xbfb8aa3b, v121
	v_add_f32_e32 v12, 1.0, v12
	v_exp_f32_e32 v18, v18
	v_div_scale_f32 v13, s[68:69], v12, v12, v119
	v_add_f32_e32 v18, 1.0, v18
	v_rcp_f32_e32 v14, v13
	v_div_scale_f32 v19, s[68:69], v18, v18, v121
	v_fma_f32 v15, -v13, v14, 1.0
	v_rcp_f32_e32 v122, v19
	v_fmac_f32_e32 v14, v15, v14
	v_div_scale_f32 v15, vcc, v119, v12, v119
	v_fma_f32 v123, -v19, v122, 1.0
	v_mul_f32_e32 v16, v15, v14
	v_fmac_f32_e32 v122, v123, v122
	v_fma_f32 v17, -v13, v16, v15
	v_fmac_f32_e32 v16, v17, v14
	v_fma_f32 v13, -v13, v16, v15
	v_div_fmas_f32 v13, v13, v14, v16
	v_div_scale_f32 v123, vcc, v121, v18, v121
	v_div_fixup_f32 v119, v13, v12, v119
	v_mul_f32_e32 v124, v123, v122
	v_mul_f32_e32 v118, v118, v119
	v_fma_f32 v125, -v19, v124, v123
	v_cvt_pk_bf16_f32 v12, v118, s0
	v_fmac_f32_e32 v124, v125, v122
	v_fma_f32 v19, -v19, v124, v123
	v_div_fmas_f32 v19, v19, v122, v124
	v_div_fixup_f32 v121, v19, v18, v121
	v_mul_f32_e32 v120, v120, v121
	v_cvt_pk_bf16_f32 v18, v120, s0
	s_add_i32 s23, s28, s22
	s_cmp_lt_i32 s23, s4
	s_cbranch_scc0 .Lconv_skipA
	global_store_short v126, v12, s[20:21]
.Lconv_skipA:
	s_cmpk_gt_i32 s22, 0x7c
	s_cbranch_scc1 .Lconv_skipB
	s_add_i32 s23, s23, 1
	s_cmp_lt_i32 s23, s4
	s_cbranch_scc0 .Lconv_skipB
	global_store_short v127, v18, s[20:21]
.Lconv_skipB:
	s_add_i32 s22, s22, 8
	v_add_u32_e32 v10, 0x880, v10
	s_add_u32 s20, s20, 0xb000
	s_addc_u32 s21, s21, 0
	s_cmpk_gt_i32 s22, 0x7d
	s_cbranch_scc0 .LBB0_28
	s_branch .LBB0_24
